# ph_up epilogue: rowss/halo preloaded at tile start, conv weights at epilogue start, LDS staging rows padded to 528B (bank conflicts), prologue vmcnt wait moved after acc zeroing
# speedup vs baseline: 1.0365x; 1.0260x over previous
.LBB0_25:
	s_mul_hi_i32 s2, s33, 0x66666667
	s_lshr_b32 s3, s2, 31
	s_ashr_i32 s2, s2, 2
	s_add_i32 s50, s2, s3
	s_mul_i32 s2, s50, 10
	s_sub_i32 s71, s33, s2
	s_cmp_gt_i32 s33, 19
	s_cselect_b64 s[72:73], -1, 0
	s_cmp_lt_i32 s33, 20
	s_cselect_b64 s[54:55], -1, 0
	s_cmp_eq_u32 s71, 0
	s_cselect_b64 s[0:1], -1, 0
	s_add_i32 s2, s33, 9
	s_cmp_lt_u32 s2, 19
	s_cselect_b64 s[2:3], -1, 0
	s_and_b64 s[2:3], s[0:1], s[2:3]
	s_cmp_eq_u32 s71, 9
	s_cselect_b64 s[52:53], -1, 0
	s_cmp_lt_i32 s33, 30
	s_cselect_b64 s[4:5], -1, 0
	s_and_b64 s[4:5], s[4:5], s[52:53]
	s_bitcmp0_b32 s50, 0
	s_mov_b32 s6, 0x3e00000
	s_cselect_b32 s27, s6, 0x7e00000
	s_mul_i32 s92, s50, 3
	s_cselect_b32 s22, 0x7e00000, s6
	s_cmp_gt_i32 s33, 9
	s_cselect_b64 s[76:77], -1, 0
	s_ashr_i32 s93, s92, 31
	s_lshl_b64 s[6:7], s[92:93], 18
	s_add_u32 s23, s6, 0x80000
	s_addc_u32 s24, s7, 0
	s_or_b64 s[2:3], s[2:3], s[4:5]
	s_andn2_b64 vcc, exec, s[2:3]
	s_mov_b64 s[2:3], -1
	s_cbranch_vccz .LBB0_300
	s_ashr_i32 s51, s50, 31
	s_waitcnt lgkmcnt(0)
	s_mov_b64 s[44:45], 0
	s_cmp_lt_i32 s71, 4
	s_mov_b64 s[60:61], 0
	s_cbranch_scc1 .LBB0_96
	s_lshl_b64 s[2:3], s[92:93], 18
	s_add_u32 s20, s2, 0x40000
	s_addc_u32 s21, s3, 0
	s_cmp_gt_i32 s71, 5
	s_cbranch_scc0 .LBB0_46
	s_cmp_gt_i32 s71, 6
	s_cbranch_scc0 .LBB0_47
	s_cmp_eq_u32 s71, 7
	s_mov_b64 s[60:61], -1
	s_cbranch_scc0 .LBB0_45
	v_readlane_b32 s4, v251, 8
	v_readlane_b32 s5, v251, 9
	s_mov_b32 s2, s87
	v_mov_b32_e32 v0, v176
	s_andn2_b64 vcc, exec, s[4:5]
	s_cbranch_vccnz .LBB0_44
	s_ashr_i32 s3, s2, 31
	v_readlane_b32 s4, v251, 4
	v_readlane_b32 s5, v251, 5
	s_add_u32 s4, s4, s2
	s_addc_u32 s5, s5, s3
	s_lshl_b64 s[2:3], s[2:3], 3
	v_readlane_b32 s8, v251, 0
	v_readlane_b32 s9, v251, 1
	s_add_u32 s2, s8, s2
	s_addc_u32 s3, s9, s3
	s_add_u32 s40, s4, s27
	s_addc_u32 s41, s5, 0
	s_add_u32 s8, s4, s20
	s_addc_u32 s9, s5, s21
	s_add_u32 s42, s8, 0x2a20000
	s_addc_u32 s43, s9, 0
	s_load_dwordx4 s[8:11], s[2:3], 0xe0
	s_add_u32 s46, s4, 0x1600000
	s_addc_u32 s47, s5, 0
	s_add_u32 s48, s4, 0x1ee00000
	s_mul_i32 s7, s50, 0x10800
	s_addc_u32 s49, s5, 0
	s_mul_hi_i32 s6, s50, 0x10800
	s_waitcnt lgkmcnt(0)
	s_add_u32 s56, s8, s7
	s_mul_i32 s13, s50, 0x5800
	s_addc_u32 s57, s9, s6
	s_mul_hi_i32 s12, s50, 0x5800
	s_add_u32 s58, s10, s13
	s_addc_u32 s59, s11, s12
	s_add_u32 s60, s58, 0x2c00
	s_addc_u32 s61, s59, 0
	s_add_u32 s62, s56, 0x2c00
	s_addc_u32 s63, s57, 0
	s_add_u32 s66, s56, 0x5800
	s_addc_u32 s67, s57, 0
	s_add_u32 s78, s56, 0x8400
	s_addc_u32 s79, s57, 0
	s_add_u32 s88, s56, 0xb000
	s_addc_u32 s89, s57, 0
	s_add_u32 s90, s56, 0xdc00
	s_addc_u32 s91, s57, 0
	s_add_u32 s96, s4, 0x1600080
	v_and_b32_e32 v3, 0xc0, v0
	v_bfe_u32 v130, v0, 4, 2
	v_and_b32_e32 v131, 15, v0
	v_ashrrev_i32_e32 v4, 1, v0
	v_and_b32_e32 v2, 0xff, v0
	v_ashrrev_i32_e32 v133, 8, v0
	v_lshl_add_u32 v134, v0, 1, 0
	v_lshl_add_u32 v134, v133, 4, v134
	v_lshlrev_b32_e32 v5, 2, v0
	s_addc_u32 s97, s5, 0
	v_and_b32_e32 v0, 31, v0
	v_and_b32_e32 v135, 0x7c, v5
	v_and_b32_e32 v136, -16, v4
	v_lshl_add_u32 v138, v3, 1, 0
	s_add_u32 s6, s40, 0x80
	v_lshlrev_b32_e32 v3, 9, v4
	v_lshlrev_b32_e32 v0, 3, v0
	s_movk_i32 s2, 0xe000
	v_lshlrev_b32_e32 v5, 9, v136
	v_lshlrev_b32_e32 v6, 1, v135
	s_addc_u32 s7, s41, 0
	v_and_or_b32 v0, v3, s2, v0
	s_add_i32 s2, 0, 0x800
	v_and_b32_e32 v132, 0xffffff80, v4
	v_add3_u32 v137, 0, v5, v6
	v_lshl_add_u32 v137, v136, 4, v137
	v_add_u32_e32 v139, s2, v0
	v_lshl_add_u32 v139, v136, 4, v139
	v_add_u32_e32 v139, 32, v139
	v_lshlrev_b32_e32 v0, 2, v2
	s_mov_b32 s16, s14
.LBB0_32:
	s_lshl_b32 s2, s16, 4
	s_and_b32 s2, s2, 0x70
	s_mul_i32 s2, s2, 22
	s_ashr_i32 s3, s16, 3
	s_add_i32 s2, s2, s3
	s_mul_hi_i32 s8, s2, 0x2e8ba2e9
	s_lshr_b32 s9, s8, 31
	s_ashr_i32 s15, s8, 5
	s_add_i32 s15, s15, s9
	s_mul_i32 s8, s15, 0xffffff50
	s_add_i32 s8, s8, s2
	v_mov_b32_e32 v2, v176
	s_lshl_b32 s2, s15, 3
	s_and_b32 s17, s3, 7
	s_ashr_i32 s18, s8, 3
	s_or_b32 s3, s2, s17
	v_readfirstlane_b32 s8, v2
	v_lshlrev_b32_e32 v3, 4, v2
	v_and_b32_e32 v4, 32, v2
	v_bfe_i32 v5, v2, 3, 25
	v_lshrrev_b32_e32 v6, 2, v2
	s_lshl_b32 s8, s8, 4
	s_lshl_b32 s19, s3, 8
	s_lshl_b32 s2, s18, 8
	v_bfi_b32 v5, -16, v5, v6
	v_bitop3_b32 v3, v3, v4, 48 bitop3:0x6c
	s_and_b32 s30, s8, 0xfffffc00
	v_and_or_b32 v3, v2, 64, v3
	v_add_u32_e32 v4, s2, v5
	s_cmp_lg_u32 0, -1
	v_lshl_or_b32 v140, v4, 11, v3
	v_add_u32_e32 v4, s19, v5
	s_cselect_b32 s8, 0, 0
	s_add_i32 s30, s30, s8
	v_add_u32_e32 v222, v131, v132
	v_add_u32_e32 v222, s19, v222
	v_ashrrev_i32_e32 v223, 31, v222
	v_lshl_add_u64 v[222:223], v[222:223], 3, s[42:43]
	global_load_dwordx2 v[224:225], v[222:223], off
	global_load_dwordx2 v[226:227], v[222:223], off offset:128
	global_load_dwordx2 v[228:229], v[222:223], off offset:256
	global_load_dwordx2 v[230:231], v[222:223], off offset:384
	global_load_dwordx2 v[232:233], v[222:223], off offset:512
	global_load_dwordx2 v[234:235], v[222:223], off offset:640
	global_load_dwordx2 v[236:237], v[222:223], off offset:768
	global_load_dwordx2 v[238:239], v[222:223], off offset:896
	v_lshl_add_u32 v242, s3, 1, v133
	v_mov_b64_e32 v[240:241], s[48:49]
	s_ashr_i32 s3, s2, 31
	v_mad_i64_i32 v[240:241], s[12:13], v242, s26, v[240:241]
	v_lshl_add_u64 v[240:241], s[2:3], 2, v[240:241]
	v_lshl_add_u64 v[240:241], v[240:241], 0, v[0:1]
	global_load_dword v243, v[240:241], off
	s_mov_b32 s12, 0x580000
	s_mov_b32 s13, 0
	v_lshl_add_u64 v[244:245], v[240:241], 0, s[12:13]
	global_load_dword v246, v[244:245], off
	s_barrier
	v_lshl_or_b32 v141, v4, 11, v3
	s_mov_b32 m0, s30
	global_load_lds_dwordx4 v141, s[40:41]
	s_add_i32 s65, s30, 0x8000
	s_mov_b32 m0, s65
	global_load_lds_dwordx4 v140, s[46:47]
	s_add_i32 s8, s30, 0x2000
	s_add_i32 s10, s30, 0xa000
	v_add_u32_e32 v142, 0x20000, v141
	s_mov_b32 m0, s8
	global_load_lds_dwordx4 v142, s[40:41]
	s_add_u32 s8, s46, 0x20000
	s_addc_u32 s9, s47, 0
	s_mov_b32 m0, s10
	global_load_lds_dwordx4 v140, s[8:9]
	s_add_i32 s8, s30, 0x4000
	s_add_i32 s10, s30, 0xc000
	v_add_u32_e32 v143, 0x40000, v141
	s_mov_b32 m0, s8
	global_load_lds_dwordx4 v143, s[40:41]
	s_add_u32 s8, s46, 0x40000
	s_addc_u32 s9, s47, 0
	s_mov_b32 m0, s10
	global_load_lds_dwordx4 v140, s[8:9]
	s_add_i32 s8, s30, 0x6000
	s_add_i32 s10, s30, 0xe000
	v_and_b32_e32 v3, 15, v2
	v_lshlrev_b32_e32 v5, 2, v2
	v_add_u32_e32 v144, 0x60000, v141
	s_mov_b32 m0, s8
	global_load_lds_dwordx4 v144, s[40:41]
	s_add_u32 s8, s46, 0x60000
	v_and_b32_e32 v4, 48, v2
	v_lshlrev_b32_e32 v3, 6, v3
	v_and_b32_e32 v5, 32, v5
	s_addc_u32 s9, s47, 0
	s_mov_b32 m0, s10
	global_load_lds_dwordx4 v140, s[8:9]
	v_bitop3_b32 v145, v3, v5, v4 bitop3:0x36
	v_lshlrev_b32_e32 v3, 7, v2
	v_lshlrev_b32_e32 v2, 6, v2
	v_and_b32_e32 v147, 0xffffc000, v2
	v_and_b32_e32 v2, 0x3c0, v2
	v_bitop3_b32 v149, v2, v5, v4 bitop3:0x36
	v_mov_b32_e32 v2, 0
	s_mov_b32 s25, 0
	v_and_b32_e32 v146, 0x6000, v3
	v_or_b32_e32 v148, 0x800, v147
	v_or_b32_e32 v150, 0x1000, v147
	v_or_b32_e32 v151, 0x1800, v147
	v_or_b32_e32 v152, 0x2000, v147
	v_or_b32_e32 v153, 0x2800, v147
	v_or_b32_e32 v154, 0x3000, v147
	v_or_b32_e32 v155, 0x3800, v147
	s_mov_b64 s[8:9], s[6:7]
	s_mov_b64 s[10:11], s[96:97]
	v_mov_b32_e32 v3, v2
	v_mov_b32_e32 v4, v2
	v_mov_b32_e32 v5, v2
	v_mov_b32_e32 v6, v2
	v_mov_b32_e32 v7, v2
	v_mov_b32_e32 v8, v2
	v_mov_b32_e32 v9, v2
	v_mov_b32_e32 v10, v2
	v_mov_b32_e32 v11, v2
	v_mov_b32_e32 v12, v2
	v_mov_b32_e32 v13, v2
	v_mov_b32_e32 v14, v2
	v_mov_b32_e32 v15, v2
	v_mov_b32_e32 v16, v2
	v_mov_b32_e32 v17, v2
	v_mov_b32_e32 v18, v2
	v_mov_b32_e32 v19, v2
	v_mov_b32_e32 v20, v2
	v_mov_b32_e32 v21, v2
	v_mov_b32_e32 v22, v2
	v_mov_b32_e32 v23, v2
	v_mov_b32_e32 v24, v2
	v_mov_b32_e32 v25, v2
	v_mov_b32_e32 v26, v2
	v_mov_b32_e32 v27, v2
	v_mov_b32_e32 v28, v2
	v_mov_b32_e32 v29, v2
	v_mov_b32_e32 v30, v2
	v_mov_b32_e32 v31, v2
	v_mov_b32_e32 v32, v2
	v_mov_b32_e32 v33, v2
	v_mov_b32_e32 v34, v2
	v_mov_b32_e32 v35, v2
	v_mov_b32_e32 v36, v2
	v_mov_b32_e32 v37, v2
	v_mov_b32_e32 v38, v2
	v_mov_b32_e32 v39, v2
	v_mov_b32_e32 v40, v2
	v_mov_b32_e32 v41, v2
	v_mov_b32_e32 v42, v2
	v_mov_b32_e32 v43, v2
	v_mov_b32_e32 v44, v2
	v_mov_b32_e32 v45, v2
	v_mov_b32_e32 v46, v2
	v_mov_b32_e32 v47, v2
	v_mov_b32_e32 v48, v2
	v_mov_b32_e32 v49, v2
	v_mov_b32_e32 v50, v2
	v_mov_b32_e32 v51, v2
	v_mov_b32_e32 v52, v2
	v_mov_b32_e32 v53, v2
	v_mov_b32_e32 v54, v2
	v_mov_b32_e32 v55, v2
	v_mov_b32_e32 v56, v2
	v_mov_b32_e32 v57, v2
	v_mov_b32_e32 v58, v2
	v_mov_b32_e32 v59, v2
	v_mov_b32_e32 v60, v2
	v_mov_b32_e32 v61, v2
	v_mov_b32_e32 v62, v2
	v_mov_b32_e32 v63, v2
	v_mov_b32_e32 v64, v2
	v_mov_b32_e32 v65, v2
	v_mov_b32_e32 v66, v2
	v_mov_b32_e32 v67, v2
	v_mov_b32_e32 v68, v2
	v_mov_b32_e32 v69, v2
	v_mov_b32_e32 v70, v2
	v_mov_b32_e32 v71, v2
	v_mov_b32_e32 v72, v2
	v_mov_b32_e32 v73, v2
	v_mov_b32_e32 v74, v2
	v_mov_b32_e32 v75, v2
	v_mov_b32_e32 v76, v2
	v_mov_b32_e32 v77, v2
	v_mov_b32_e32 v78, v2
	v_mov_b32_e32 v79, v2
	v_mov_b32_e32 v80, v2
	v_mov_b32_e32 v81, v2
	v_mov_b32_e32 v82, v2
	v_mov_b32_e32 v83, v2
	v_mov_b32_e32 v84, v2
	v_mov_b32_e32 v85, v2
	v_mov_b32_e32 v86, v2
	v_mov_b32_e32 v87, v2
	v_mov_b32_e32 v88, v2
	v_mov_b32_e32 v89, v2
	v_mov_b32_e32 v90, v2
	v_mov_b32_e32 v91, v2
	v_mov_b32_e32 v92, v2
	v_mov_b32_e32 v93, v2
	v_mov_b32_e32 v94, v2
	v_mov_b32_e32 v95, v2
	v_mov_b32_e32 v96, v2
	v_mov_b32_e32 v97, v2
	v_mov_b32_e32 v98, v2
	v_mov_b32_e32 v99, v2
	v_mov_b32_e32 v100, v2
	v_mov_b32_e32 v101, v2
	v_mov_b32_e32 v102, v2
	v_mov_b32_e32 v103, v2
	v_mov_b32_e32 v104, v2
	v_mov_b32_e32 v105, v2
	v_mov_b32_e32 v106, v2
	v_mov_b32_e32 v107, v2
	v_mov_b32_e32 v108, v2
	v_mov_b32_e32 v109, v2
	v_mov_b32_e32 v110, v2
	v_mov_b32_e32 v111, v2
	v_mov_b32_e32 v112, v2
	v_mov_b32_e32 v113, v2
	v_mov_b32_e32 v114, v2
	v_mov_b32_e32 v115, v2
	v_mov_b32_e32 v116, v2
	v_mov_b32_e32 v117, v2
	v_mov_b32_e32 v118, v2
	v_mov_b32_e32 v119, v2
	v_mov_b32_e32 v120, v2
	v_mov_b32_e32 v121, v2
	v_mov_b32_e32 v122, v2
	v_mov_b32_e32 v123, v2
	v_mov_b32_e32 v124, v2
	v_mov_b32_e32 v125, v2
	v_mov_b32_e32 v126, v2
	v_mov_b32_e32 v127, v2
	v_mov_b32_e32 v128, v2
	v_mov_b32_e32 v129, v2
	s_waitcnt vmcnt(0)
	s_barrier
	s_branch .LBB0_34

.LBB0_38:
	s_load_dword s99, s[74:75], 0x0
	v_lshl_or_b32 v202, s18, 7, v135
	v_ashrrev_i32_e32 v203, 31, v202
	v_lshlrev_b64 v[202:203], 2, v[202:203]
	v_lshl_add_u64 v[204:205], s[56:57], 0, v[202:203]
	v_lshl_add_u64 v[206:207], s[62:63], 0, v[202:203]
	global_load_dwordx4 v[156:159], v[204:205], off
	global_load_dwordx4 v[160:163], v[206:207], off
	v_lshl_add_u64 v[204:205], s[66:67], 0, v[202:203]
	v_lshl_add_u64 v[206:207], s[78:79], 0, v[202:203]
	global_load_dwordx4 v[164:167], v[204:205], off
	global_load_dwordx4 v[168:171], v[206:207], off
	v_lshl_add_u64 v[204:205], s[88:89], 0, v[202:203]
	v_lshl_add_u64 v[206:207], s[90:91], 0, v[202:203]
	global_load_dwordx4 v[172:175], v[204:205], off
	global_load_dwordx4 v[190:193], v[206:207], off
	v_lshl_add_u64 v[204:205], s[58:59], 0, v[202:203]
	v_lshl_add_u64 v[206:207], s[60:61], 0, v[202:203]
	global_load_dwordx4 v[194:197], v[204:205], off
	global_load_dwordx4 v[198:201], v[206:207], off
	v_mov_b32_e32 v140, v130
	v_mov_b32_e32 v141, v131
	s_cmp_eq_u32 s17, 0
	v_add_u32_e32 v141, v141, v132
	v_mov_b32_e32 v142, v224
	v_mov_b32_e32 v143, v225
	v_lshlrev_b32_e32 v140, 4, v140
	v_ffbh_u32_e32 v144, v143
	v_min_u32_e32 v144, 32, v144
	v_lshlrev_b64 v[142:143], v144, v[142:143]
	v_min_u32_e32 v142, 1, v142
	v_or_b32_e32 v142, v143, v142
	v_cvt_f32_u32_e32 v142, v142
	v_sub_u32_e32 v143, 32, v144
	v_ldexp_f32 v142, v142, v143
	v_fmamk_f32 v142, v142, 0x2e800000, v177
	v_cmp_gt_f32_e32 vcc, s34, v142
	v_mul_f32_e32 v143, 0x4b800000, v142
	s_nop 0
	v_cndmask_b32_e32 v142, v142, v143, vcc
	v_rsq_f32_e32 v142, v142
	s_nop 0
	v_mul_f32_e32 v143, 0x45800000, v142
	v_cndmask_b32_e32 v142, v142, v143, vcc
	v_mul_u32_u24_e32 v143, 0x210, v141
	v_add3_u32 v143, v138, v143, v140
	v_pk_mul_f32 v[128:129], v[128:129], v[142:143] op_sel_hi:[1,0]
	v_pk_mul_f32 v[126:127], v[126:127], v[142:143] op_sel_hi:[1,0]
	v_pk_mul_f32 v[144:145], v[124:125], v[142:143] op_sel_hi:[1,0]
	v_pk_mul_f32 v[124:125], v[122:123], v[142:143] op_sel_hi:[1,0]
	v_cvt_pk_bf16_f32 v122, v126, v127
	v_cvt_pk_bf16_f32 v123, v128, v129
	v_cvt_pk_bf16_f32 v124, v124, v125
	v_cvt_pk_bf16_f32 v125, v144, v145
	ds_write_b128 v143, v[122:125] offset:2080
	v_pk_mul_f32 v[120:121], v[120:121], v[142:143] op_sel_hi:[1,0]
	v_pk_mul_f32 v[118:119], v[118:119], v[142:143] op_sel_hi:[1,0]
	v_pk_mul_f32 v[122:123], v[116:117], v[142:143] op_sel_hi:[1,0]
	v_pk_mul_f32 v[116:117], v[114:115], v[142:143] op_sel_hi:[1,0]
	v_cvt_pk_bf16_f32 v114, v118, v119
	v_cvt_pk_bf16_f32 v115, v120, v121
	v_cvt_pk_bf16_f32 v116, v116, v117
	v_cvt_pk_bf16_f32 v117, v122, v123
	ds_write_b128 v143, v[114:117] offset:2144
	v_add_u32_e32 v116, 16, v141
	v_mov_b32_e32 v114, v226
	v_mov_b32_e32 v115, v227
	v_ffbh_u32_e32 v117, v115
	v_min_u32_e32 v117, 32, v117
	v_lshlrev_b64 v[114:115], v117, v[114:115]
	v_min_u32_e32 v114, 1, v114
	v_or_b32_e32 v114, v115, v114
	v_cvt_f32_u32_e32 v114, v114
	v_sub_u32_e32 v115, 32, v117
	v_ldexp_f32 v114, v114, v115
	v_fmamk_f32 v114, v114, 0x2e800000, v177
	v_cmp_gt_f32_e32 vcc, s34, v114
	v_mul_f32_e32 v115, 0x4b800000, v114
	s_nop 0
	v_cndmask_b32_e32 v114, v114, v115, vcc
	v_rsq_f32_e32 v114, v114
	s_nop 0
	v_mul_f32_e32 v115, 0x45800000, v114
	v_cndmask_b32_e32 v114, v114, v115, vcc
	v_mul_u32_u24_e32 v115, 0x210, v116
	v_add3_u32 v115, v138, v115, v140
	v_pk_mul_f32 v[112:113], v[112:113], v[114:115] op_sel_hi:[1,0]
	v_pk_mul_f32 v[110:111], v[110:111], v[114:115] op_sel_hi:[1,0]
	v_pk_mul_f32 v[116:117], v[108:109], v[114:115] op_sel_hi:[1,0]
	v_pk_mul_f32 v[108:109], v[106:107], v[114:115] op_sel_hi:[1,0]
	v_cvt_pk_bf16_f32 v106, v110, v111
	v_cvt_pk_bf16_f32 v107, v112, v113
	v_cvt_pk_bf16_f32 v108, v108, v109
	v_cvt_pk_bf16_f32 v109, v116, v117
	ds_write_b128 v115, v[106:109] offset:2080
	v_pk_mul_f32 v[104:105], v[104:105], v[114:115] op_sel_hi:[1,0]
	v_pk_mul_f32 v[102:103], v[102:103], v[114:115] op_sel_hi:[1,0]
	v_pk_mul_f32 v[106:107], v[100:101], v[114:115] op_sel_hi:[1,0]
	v_pk_mul_f32 v[100:101], v[98:99], v[114:115] op_sel_hi:[1,0]
	v_cvt_pk_bf16_f32 v98, v102, v103
	v_cvt_pk_bf16_f32 v99, v104, v105
	v_cvt_pk_bf16_f32 v100, v100, v101
	v_cvt_pk_bf16_f32 v101, v106, v107
	ds_write_b128 v115, v[98:101] offset:2144
	v_add_u32_e32 v100, 32, v141
	v_mov_b32_e32 v98, v228
	v_mov_b32_e32 v99, v229
	v_ffbh_u32_e32 v101, v99
	v_min_u32_e32 v101, 32, v101
	v_lshlrev_b64 v[98:99], v101, v[98:99]
	v_min_u32_e32 v98, 1, v98
	v_or_b32_e32 v98, v99, v98
	v_cvt_f32_u32_e32 v98, v98
	v_sub_u32_e32 v99, 32, v101
	v_ldexp_f32 v98, v98, v99
	v_fmamk_f32 v98, v98, 0x2e800000, v177
	v_cmp_gt_f32_e32 vcc, s34, v98
	v_mul_f32_e32 v99, 0x4b800000, v98
	s_nop 0
	v_cndmask_b32_e32 v98, v98, v99, vcc
	v_rsq_f32_e32 v98, v98
	s_nop 0
	v_mul_f32_e32 v99, 0x45800000, v98
	v_cndmask_b32_e32 v98, v98, v99, vcc
	v_mul_u32_u24_e32 v99, 0x210, v100
	v_add3_u32 v99, v138, v99, v140
	v_pk_mul_f32 v[96:97], v[96:97], v[98:99] op_sel_hi:[1,0]
	v_pk_mul_f32 v[94:95], v[94:95], v[98:99] op_sel_hi:[1,0]
	v_pk_mul_f32 v[100:101], v[92:93], v[98:99] op_sel_hi:[1,0]
	v_pk_mul_f32 v[92:93], v[90:91], v[98:99] op_sel_hi:[1,0]
	v_cvt_pk_bf16_f32 v90, v94, v95
	v_cvt_pk_bf16_f32 v91, v96, v97
	v_cvt_pk_bf16_f32 v92, v92, v93
	v_cvt_pk_bf16_f32 v93, v100, v101
	ds_write_b128 v99, v[90:93] offset:2080
	v_pk_mul_f32 v[88:89], v[88:89], v[98:99] op_sel_hi:[1,0]
	v_pk_mul_f32 v[86:87], v[86:87], v[98:99] op_sel_hi:[1,0]
	v_pk_mul_f32 v[90:91], v[84:85], v[98:99] op_sel_hi:[1,0]
	v_pk_mul_f32 v[84:85], v[82:83], v[98:99] op_sel_hi:[1,0]
	v_cvt_pk_bf16_f32 v82, v86, v87
	v_cvt_pk_bf16_f32 v83, v88, v89
	v_cvt_pk_bf16_f32 v84, v84, v85
	v_cvt_pk_bf16_f32 v85, v90, v91
	ds_write_b128 v99, v[82:85] offset:2144
	v_add_u32_e32 v84, 48, v141
	v_mov_b32_e32 v82, v230
	v_mov_b32_e32 v83, v231
	v_ffbh_u32_e32 v85, v83
	v_min_u32_e32 v85, 32, v85
	v_lshlrev_b64 v[82:83], v85, v[82:83]
	v_min_u32_e32 v82, 1, v82
	v_or_b32_e32 v82, v83, v82
	v_cvt_f32_u32_e32 v82, v82
	v_sub_u32_e32 v83, 32, v85
	v_ldexp_f32 v82, v82, v83
	v_fmamk_f32 v82, v82, 0x2e800000, v177
	v_cmp_gt_f32_e32 vcc, s34, v82
	v_mul_f32_e32 v83, 0x4b800000, v82
	s_nop 0
	v_cndmask_b32_e32 v82, v82, v83, vcc
	v_rsq_f32_e32 v82, v82
	s_nop 0
	v_mul_f32_e32 v83, 0x45800000, v82
	v_cndmask_b32_e32 v82, v82, v83, vcc
	v_mul_u32_u24_e32 v83, 0x210, v84
	v_add3_u32 v83, v138, v83, v140
	v_pk_mul_f32 v[80:81], v[80:81], v[82:83] op_sel_hi:[1,0]
	v_pk_mul_f32 v[78:79], v[78:79], v[82:83] op_sel_hi:[1,0]
	v_pk_mul_f32 v[84:85], v[76:77], v[82:83] op_sel_hi:[1,0]
	v_pk_mul_f32 v[76:77], v[74:75], v[82:83] op_sel_hi:[1,0]
	v_cvt_pk_bf16_f32 v74, v78, v79
	v_cvt_pk_bf16_f32 v75, v80, v81
	v_cvt_pk_bf16_f32 v76, v76, v77
	v_cvt_pk_bf16_f32 v77, v84, v85
	ds_write_b128 v83, v[74:77] offset:2080
	v_pk_mul_f32 v[72:73], v[72:73], v[82:83] op_sel_hi:[1,0]
	v_pk_mul_f32 v[70:71], v[70:71], v[82:83] op_sel_hi:[1,0]
	v_pk_mul_f32 v[74:75], v[68:69], v[82:83] op_sel_hi:[1,0]
	v_pk_mul_f32 v[68:69], v[66:67], v[82:83] op_sel_hi:[1,0]
	v_cvt_pk_bf16_f32 v66, v70, v71
	v_cvt_pk_bf16_f32 v67, v72, v73
	v_cvt_pk_bf16_f32 v68, v68, v69
	v_cvt_pk_bf16_f32 v69, v74, v75
	ds_write_b128 v83, v[66:69] offset:2144
	v_add_u32_e32 v68, 64, v141
	v_mov_b32_e32 v66, v232
	v_mov_b32_e32 v67, v233
	v_ffbh_u32_e32 v69, v67
	v_min_u32_e32 v69, 32, v69
	v_lshlrev_b64 v[66:67], v69, v[66:67]
	v_min_u32_e32 v66, 1, v66
	v_or_b32_e32 v66, v67, v66
	v_cvt_f32_u32_e32 v66, v66
	v_sub_u32_e32 v67, 32, v69
	v_ldexp_f32 v66, v66, v67
	v_fmamk_f32 v66, v66, 0x2e800000, v177
	v_cmp_gt_f32_e32 vcc, s34, v66
	v_mul_f32_e32 v67, 0x4b800000, v66
	s_nop 0
	v_cndmask_b32_e32 v66, v66, v67, vcc
	v_rsq_f32_e32 v66, v66
	s_nop 0
	v_mul_f32_e32 v67, 0x45800000, v66
	v_cndmask_b32_e32 v66, v66, v67, vcc
	v_mul_u32_u24_e32 v67, 0x210, v68
	v_add3_u32 v67, v138, v67, v140
	v_pk_mul_f32 v[64:65], v[64:65], v[66:67] op_sel_hi:[1,0]
	v_pk_mul_f32 v[62:63], v[62:63], v[66:67] op_sel_hi:[1,0]
	v_pk_mul_f32 v[68:69], v[60:61], v[66:67] op_sel_hi:[1,0]
	v_pk_mul_f32 v[60:61], v[58:59], v[66:67] op_sel_hi:[1,0]
	v_cvt_pk_bf16_f32 v58, v62, v63
	v_cvt_pk_bf16_f32 v59, v64, v65
	v_cvt_pk_bf16_f32 v60, v60, v61
	v_cvt_pk_bf16_f32 v61, v68, v69
	ds_write_b128 v67, v[58:61] offset:2080
	v_pk_mul_f32 v[56:57], v[56:57], v[66:67] op_sel_hi:[1,0]
	v_pk_mul_f32 v[54:55], v[54:55], v[66:67] op_sel_hi:[1,0]
	v_pk_mul_f32 v[58:59], v[52:53], v[66:67] op_sel_hi:[1,0]
	v_pk_mul_f32 v[52:53], v[50:51], v[66:67] op_sel_hi:[1,0]
	v_cvt_pk_bf16_f32 v50, v54, v55
	v_cvt_pk_bf16_f32 v51, v56, v57
	v_cvt_pk_bf16_f32 v52, v52, v53
	v_cvt_pk_bf16_f32 v53, v58, v59
	ds_write_b128 v67, v[50:53] offset:2144
	v_add_u32_e32 v52, 0x50, v141
	v_mov_b32_e32 v50, v234
	v_mov_b32_e32 v51, v235
	v_ffbh_u32_e32 v53, v51
	v_min_u32_e32 v53, 32, v53
	v_lshlrev_b64 v[50:51], v53, v[50:51]
	v_min_u32_e32 v50, 1, v50
	v_or_b32_e32 v50, v51, v50
	v_cvt_f32_u32_e32 v50, v50
	v_sub_u32_e32 v51, 32, v53
	v_ldexp_f32 v50, v50, v51
	v_fmamk_f32 v50, v50, 0x2e800000, v177
	v_cmp_gt_f32_e32 vcc, s34, v50
	v_mul_f32_e32 v51, 0x4b800000, v50
	s_nop 0
	v_cndmask_b32_e32 v50, v50, v51, vcc
	v_rsq_f32_e32 v50, v50
	s_nop 0
	v_mul_f32_e32 v51, 0x45800000, v50
	v_cndmask_b32_e32 v50, v50, v51, vcc
	v_mul_u32_u24_e32 v51, 0x210, v52
	v_add3_u32 v51, v138, v51, v140
	v_pk_mul_f32 v[48:49], v[48:49], v[50:51] op_sel_hi:[1,0]
	v_pk_mul_f32 v[46:47], v[46:47], v[50:51] op_sel_hi:[1,0]
	v_pk_mul_f32 v[52:53], v[44:45], v[50:51] op_sel_hi:[1,0]
	v_pk_mul_f32 v[44:45], v[42:43], v[50:51] op_sel_hi:[1,0]
	v_cvt_pk_bf16_f32 v42, v46, v47
	v_cvt_pk_bf16_f32 v43, v48, v49
	v_cvt_pk_bf16_f32 v44, v44, v45
	v_cvt_pk_bf16_f32 v45, v52, v53
	ds_write_b128 v51, v[42:45] offset:2080
	v_pk_mul_f32 v[40:41], v[40:41], v[50:51] op_sel_hi:[1,0]
	v_pk_mul_f32 v[38:39], v[38:39], v[50:51] op_sel_hi:[1,0]
	v_pk_mul_f32 v[42:43], v[36:37], v[50:51] op_sel_hi:[1,0]
	v_pk_mul_f32 v[36:37], v[34:35], v[50:51] op_sel_hi:[1,0]
	v_cvt_pk_bf16_f32 v34, v38, v39
	v_cvt_pk_bf16_f32 v35, v40, v41
	v_cvt_pk_bf16_f32 v36, v36, v37
	v_cvt_pk_bf16_f32 v37, v42, v43
	ds_write_b128 v51, v[34:37] offset:2144
	v_add_u32_e32 v36, 0x60, v141
	v_mov_b32_e32 v34, v236
	v_mov_b32_e32 v35, v237
	v_ffbh_u32_e32 v37, v35
	v_min_u32_e32 v37, 32, v37
	v_lshlrev_b64 v[34:35], v37, v[34:35]
	v_min_u32_e32 v34, 1, v34
	v_or_b32_e32 v34, v35, v34
	v_cvt_f32_u32_e32 v34, v34
	v_sub_u32_e32 v35, 32, v37
	v_ldexp_f32 v34, v34, v35
	v_fmamk_f32 v34, v34, 0x2e800000, v177
	v_cmp_gt_f32_e32 vcc, s34, v34
	v_mul_f32_e32 v35, 0x4b800000, v34
	s_nop 0
	v_cndmask_b32_e32 v34, v34, v35, vcc
	v_rsq_f32_e32 v34, v34
	s_nop 0
	v_mul_f32_e32 v35, 0x45800000, v34
	v_cndmask_b32_e32 v34, v34, v35, vcc
	v_mul_u32_u24_e32 v35, 0x210, v36
	v_add3_u32 v35, v138, v35, v140
	v_pk_mul_f32 v[32:33], v[32:33], v[34:35] op_sel_hi:[1,0]
	v_pk_mul_f32 v[30:31], v[30:31], v[34:35] op_sel_hi:[1,0]
	v_pk_mul_f32 v[36:37], v[28:29], v[34:35] op_sel_hi:[1,0]
	v_pk_mul_f32 v[28:29], v[26:27], v[34:35] op_sel_hi:[1,0]
	v_cvt_pk_bf16_f32 v26, v30, v31
	v_cvt_pk_bf16_f32 v27, v32, v33
	v_cvt_pk_bf16_f32 v28, v28, v29
	v_cvt_pk_bf16_f32 v29, v36, v37
	ds_write_b128 v35, v[26:29] offset:2080
	v_pk_mul_f32 v[24:25], v[24:25], v[34:35] op_sel_hi:[1,0]
	v_pk_mul_f32 v[22:23], v[22:23], v[34:35] op_sel_hi:[1,0]
	v_pk_mul_f32 v[26:27], v[20:21], v[34:35] op_sel_hi:[1,0]
	v_pk_mul_f32 v[20:21], v[18:19], v[34:35] op_sel_hi:[1,0]
	v_cvt_pk_bf16_f32 v18, v22, v23
	v_cvt_pk_bf16_f32 v19, v24, v25
	v_cvt_pk_bf16_f32 v20, v20, v21
	v_cvt_pk_bf16_f32 v21, v26, v27
	ds_write_b128 v35, v[18:21] offset:2144
	v_add_u32_e32 v20, 0x70, v141
	v_mov_b32_e32 v18, v238
	v_mov_b32_e32 v19, v239
	v_ffbh_u32_e32 v21, v19
	v_min_u32_e32 v21, 32, v21
	v_lshlrev_b64 v[18:19], v21, v[18:19]
	v_min_u32_e32 v18, 1, v18
	v_or_b32_e32 v18, v19, v18
	v_cvt_f32_u32_e32 v18, v18
	v_sub_u32_e32 v19, 32, v21
	v_ldexp_f32 v18, v18, v19
	v_fmamk_f32 v18, v18, 0x2e800000, v177
	v_cmp_gt_f32_e32 vcc, s34, v18
	v_mul_f32_e32 v19, 0x4b800000, v18
	s_nop 0
	v_cndmask_b32_e32 v18, v18, v19, vcc
	v_rsq_f32_e32 v18, v18
	s_nop 0
	v_mul_f32_e32 v19, 0x45800000, v18
	v_cndmask_b32_e32 v18, v18, v19, vcc
	v_mul_u32_u24_e32 v19, 0x210, v20
	v_add3_u32 v19, v138, v19, v140
	v_pk_mul_f32 v[16:17], v[16:17], v[18:19] op_sel_hi:[1,0]
	v_pk_mul_f32 v[14:15], v[14:15], v[18:19] op_sel_hi:[1,0]
	v_pk_mul_f32 v[20:21], v[12:13], v[18:19] op_sel_hi:[1,0]
	v_pk_mul_f32 v[12:13], v[10:11], v[18:19] op_sel_hi:[1,0]
	v_cvt_pk_bf16_f32 v10, v14, v15
	v_cvt_pk_bf16_f32 v11, v16, v17
	v_cvt_pk_bf16_f32 v12, v12, v13
	v_cvt_pk_bf16_f32 v13, v20, v21
	ds_write_b128 v19, v[10:13] offset:2080
	v_pk_mul_f32 v[8:9], v[8:9], v[18:19] op_sel_hi:[1,0]
	v_pk_mul_f32 v[6:7], v[6:7], v[18:19] op_sel_hi:[1,0]
	v_pk_mul_f32 v[10:11], v[4:5], v[18:19] op_sel_hi:[1,0]
	v_pk_mul_f32 v[4:5], v[2:3], v[18:19] op_sel_hi:[1,0]
	v_cvt_pk_bf16_f32 v2, v6, v7
	v_cvt_pk_bf16_f32 v3, v8, v9
	v_cvt_pk_bf16_f32 v4, v4, v5
	v_cvt_pk_bf16_f32 v5, v10, v11
	ds_write_b128 v19, v[2:5] offset:2144
	s_cbranch_scc1 .LBB0_40
	v_add_f32_e32 v2, v243, v246
	s_branch .LBB0_41

.LBB0_41:
	v_lshl_or_b32 v42, s18, 7, v135
	v_bfe_u32 v3, v2, 16, 1
	v_ashrrev_i32_e32 v43, 31, v42
	v_add3_u32 v2, v2, v3, s36
	ds_write_b16_d16_hi v134, v2 offset:1024
	s_waitcnt lgkmcnt(0)
	s_barrier
	ds_read2_b64 v[34:37], v137 offset0:128 offset1:160
	ds_read2_b64 v[38:41], v137 offset0:194 offset1:226
	s_lshl_b32 s2, s15, 11
	s_lshl_b32 s3, s17, 8
	s_or_b32 s2, s3, s2
	v_add_u32_e32 v44, s2, v136
	v_lshlrev_b64 v[42:43], 1, v[42:43]
	s_movk_i32 s2, 0x1600
	v_mad_i64_i32 v[42:43], s[2:3], v44, s2, v[42:43]
	v_lshl_add_u64 v[42:43], s[4:5], 0, v[42:43]
	s_mov_b64 s[2:3], 0
	v_mov_b32_e32 v62, v139
	s_waitcnt vmcnt(0)
	v_mov_b32_e32 v2, v156
	v_mov_b32_e32 v3, v157
	v_mov_b32_e32 v4, v158
	v_mov_b32_e32 v5, v159
	v_mov_b32_e32 v6, v160
	v_mov_b32_e32 v7, v161
	v_mov_b32_e32 v8, v162
	v_mov_b32_e32 v9, v163
	v_mov_b32_e32 v10, v164
	v_mov_b32_e32 v11, v165
	v_mov_b32_e32 v12, v166
	v_mov_b32_e32 v13, v167
	v_mov_b32_e32 v14, v168
	v_mov_b32_e32 v15, v169
	v_mov_b32_e32 v16, v170
	v_mov_b32_e32 v17, v171
	v_mov_b32_e32 v18, v172
	v_mov_b32_e32 v19, v173
	v_mov_b32_e32 v20, v174
	v_mov_b32_e32 v21, v175
	v_mov_b32_e32 v22, v190
	v_mov_b32_e32 v23, v191
	v_mov_b32_e32 v24, v192
	v_mov_b32_e32 v25, v193
	v_mov_b32_e32 v26, v194
	v_mov_b32_e32 v27, v195
	v_mov_b32_e32 v28, v196
	v_mov_b32_e32 v29, v197
	v_mov_b32_e32 v30, v198
	v_mov_b32_e32 v31, v199
	v_mov_b32_e32 v32, v200
	v_mov_b32_e32 v33, v201
.LBB0_42:
	ds_read2_b64 v[50:53], v62 offset1:32
	s_waitcnt lgkmcnt(2)
	v_lshlrev_b32_e32 v44, 16, v34
	v_and_b32_e32 v45, 0xffff0000, v34
	s_waitcnt lgkmcnt(1)
	v_lshlrev_b32_e32 v48, 16, v38
	v_and_b32_e32 v49, 0xffff0000, v38
	v_pk_fma_f32 v[44:45], v[2:3], v[44:45], v[26:27]
	s_waitcnt lgkmcnt(0)
	v_lshlrev_b32_e32 v46, 16, v50
	v_and_b32_e32 v47, 0xffff0000, v50
	v_pk_fma_f32 v[44:45], v[10:11], v[48:49], v[44:45]
	v_lshlrev_b32_e32 v58, 16, v36
	v_pk_fma_f32 v[44:45], v[18:19], v[46:47], v[44:45]
	v_and_b32_e32 v59, 0xffff0000, v36
	v_pk_mul_f32 v[54:55], v[44:45], v[44:45]
	v_lshlrev_b32_e32 v60, 16, v40
	v_fmamk_f32 v34, v54, 0xbdd2d3e8, v178
	v_mul_f32_e32 v34, v44, v34
	v_exp_f32_e32 v34, v34
	v_and_b32_e32 v61, 0xffff0000, v40
	v_pk_fma_f32 v[58:59], v[6:7], v[58:59], v[30:31]
	v_lshlrev_b32_e32 v56, 16, v52
	v_add_f32_e32 v34, 1.0, v34
	v_rcp_f32_e32 v54, v34
	v_fmamk_f32 v34, v55, 0xbdd2d3e8, v178
	v_mul_f32_e32 v34, v45, v34
	v_exp_f32_e32 v34, v34
	v_and_b32_e32 v57, 0xffff0000, v52
	v_pk_fma_f32 v[58:59], v[14:15], v[60:61], v[58:59]
	v_lshlrev_b32_e32 v38, 16, v51
	v_add_f32_e32 v34, 1.0, v34
	v_rcp_f32_e32 v55, v34
	v_pk_fma_f32 v[58:59], v[22:23], v[56:57], v[58:59]
	v_lshlrev_b32_e32 v64, 16, v41
	v_and_b32_e32 v65, 0xffff0000, v41
	v_pk_mul_f32 v[44:45], v[44:45], v[54:55]
	v_lshlrev_b32_e32 v54, 16, v37
	v_pk_mul_f32 v[44:45], v[58:59], v[44:45]
	v_lshlrev_b32_e32 v58, 16, v39
	v_cvt_pk_bf16_f32 v34, v44, v45
	v_lshlrev_b32_e32 v44, 16, v35
	v_and_b32_e32 v45, 0xffff0000, v35
	v_and_b32_e32 v59, 0xffff0000, v39
	v_pk_fma_f32 v[44:45], v[4:5], v[44:45], v[28:29]
	v_and_b32_e32 v39, 0xffff0000, v51
	v_pk_fma_f32 v[44:45], v[12:13], v[58:59], v[44:45]
	v_and_b32_e32 v55, 0xffff0000, v37
	v_pk_fma_f32 v[44:45], v[20:21], v[38:39], v[44:45]
	v_lshlrev_b32_e32 v40, 16, v53
	v_pk_mul_f32 v[50:51], v[44:45], v[44:45]
	v_and_b32_e32 v41, 0xffff0000, v53
	v_fmamk_f32 v35, v50, 0xbdd2d3e8, v178
	v_mul_f32_e32 v35, v44, v35
	v_exp_f32_e32 v35, v35
	v_pk_fma_f32 v[52:53], v[8:9], v[54:55], v[32:33]
	s_mov_b32 s8, 0x13e00000
	v_pk_fma_f32 v[52:53], v[16:17], v[64:65], v[52:53]
	v_add_f32_e32 v35, 1.0, v35
	v_rcp_f32_e32 v36, v35
	v_fmamk_f32 v35, v51, 0xbdd2d3e8, v178
	v_mul_f32_e32 v35, v45, v35
	v_exp_f32_e32 v35, v35
	v_pk_fma_f32 v[52:53], v[24:25], v[40:41], v[52:53]
	v_pk_fma_f32 v[48:49], v[2:3], v[48:49], v[26:27]
	v_pk_fma_f32 v[60:61], v[6:7], v[60:61], v[30:31]
	v_add_f32_e32 v35, 1.0, v35
	v_rcp_f32_e32 v37, v35
	v_pk_fma_f32 v[48:49], v[10:11], v[46:47], v[48:49]
	v_pk_fma_f32 v[60:61], v[14:15], v[56:57], v[60:61]
	v_pk_fma_f32 v[64:65], v[8:9], v[64:65], v[32:33]
	v_pk_mul_f32 v[36:37], v[44:45], v[36:37]
	v_lshl_add_u64 v[44:45], v[42:43], 0, s[2:3]
	v_pk_mul_f32 v[36:37], v[52:53], v[36:37]
	v_pk_fma_f32 v[64:65], v[16:17], v[40:41], v[64:65]
	v_cvt_pk_bf16_f32 v35, v36, v37
	v_add_co_u32_e32 v36, vcc, s8, v44
	s_mov_b32 s8, 0x13e01000
	s_nop 0
	v_addc_co_u32_e32 v37, vcc, 0, v45, vcc
	global_store_dwordx2 v[36:37], v[34:35], off
	ds_read2_b64 v[34:37], v62 offset0:66 offset1:98
	v_pk_fma_f32 v[46:47], v[2:3], v[46:47], v[26:27]
	v_pk_fma_f32 v[56:57], v[6:7], v[56:57], v[30:31]
	v_pk_fma_f32 v[40:41], v[8:9], v[40:41], v[32:33]
	s_add_u32 s2, s2, 0x5800
	s_waitcnt lgkmcnt(0)
	v_lshlrev_b32_e32 v54, 16, v34
	v_and_b32_e32 v55, 0xffff0000, v34
	v_pk_fma_f32 v[48:49], v[18:19], v[54:55], v[48:49]
	v_lshlrev_b32_e32 v52, 16, v36
	v_pk_mul_f32 v[50:51], v[48:49], v[48:49]
	v_and_b32_e32 v53, 0xffff0000, v36
	v_fmamk_f32 v34, v50, 0xbdd2d3e8, v178
	v_mul_f32_e32 v34, v48, v34
	v_exp_f32_e32 v34, v34
	v_pk_fma_f32 v[60:61], v[22:23], v[52:53], v[60:61]
	v_pk_fma_f32 v[46:47], v[10:11], v[54:55], v[46:47]
	v_pk_fma_f32 v[56:57], v[14:15], v[52:53], v[56:57]
	v_add_f32_e32 v34, 1.0, v34
	v_rcp_f32_e32 v50, v34
	v_fmamk_f32 v34, v51, 0xbdd2d3e8, v178
	v_mul_f32_e32 v34, v49, v34
	v_exp_f32_e32 v34, v34
	v_pk_fma_f32 v[54:55], v[2:3], v[54:55], v[26:27]
	v_pk_fma_f32 v[52:53], v[6:7], v[52:53], v[30:31]
	s_addc_u32 s3, s3, 0
	v_add_f32_e32 v34, 1.0, v34
	v_rcp_f32_e32 v51, v34
	s_cmp_eq_u32 s2, 0x16000
	v_pk_mul_f32 v[48:49], v[48:49], v[50:51]
	s_nop 0
	v_pk_mul_f32 v[48:49], v[60:61], v[48:49]
	v_lshlrev_b32_e32 v50, 16, v35
	v_cvt_pk_bf16_f32 v34, v48, v49
	v_pk_fma_f32 v[48:49], v[4:5], v[58:59], v[28:29]
	v_and_b32_e32 v51, 0xffff0000, v35
	v_pk_fma_f32 v[48:49], v[12:13], v[38:39], v[48:49]
	v_pk_fma_f32 v[38:39], v[4:5], v[38:39], v[28:29]
	v_pk_fma_f32 v[58:59], v[20:21], v[50:51], v[48:49]
	v_lshlrev_b32_e32 v48, 16, v37
	v_pk_mul_f32 v[60:61], v[58:59], v[58:59]
	v_and_b32_e32 v49, 0xffff0000, v37
	v_fmamk_f32 v35, v60, 0xbdd2d3e8, v178
	v_mul_f32_e32 v35, v58, v35
	v_exp_f32_e32 v35, v35
	v_pk_fma_f32 v[64:65], v[24:25], v[48:49], v[64:65]
	v_pk_fma_f32 v[38:39], v[12:13], v[50:51], v[38:39]
	v_pk_fma_f32 v[40:41], v[16:17], v[48:49], v[40:41]
	v_add_f32_e32 v35, 1.0, v35
	v_rcp_f32_e32 v36, v35
	v_fmamk_f32 v35, v61, 0xbdd2d3e8, v178
	v_mul_f32_e32 v35, v59, v35
	v_exp_f32_e32 v35, v35
	v_pk_fma_f32 v[50:51], v[4:5], v[50:51], v[28:29]
	v_pk_fma_f32 v[48:49], v[8:9], v[48:49], v[32:33]
	v_add_f32_e32 v35, 1.0, v35
	v_rcp_f32_e32 v37, v35
	s_nop 0
	v_pk_mul_f32 v[36:37], v[58:59], v[36:37]
	s_nop 0
	v_pk_mul_f32 v[36:37], v[64:65], v[36:37]
	s_nop 0
	v_cvt_pk_bf16_f32 v35, v36, v37
	v_add_co_u32_e32 v36, vcc, s8, v44
	s_mov_b32 s8, 0x13e02000
	s_nop 0
	v_addc_co_u32_e32 v37, vcc, 0, v45, vcc
	global_store_dwordx2 v[36:37], v[34:35], off offset:1536
	ds_read2_b64 v[34:37], v62 offset0:132 offset1:164
	s_waitcnt lgkmcnt(0)
	v_lshlrev_b32_e32 v60, 16, v34
	v_and_b32_e32 v61, 0xffff0000, v34
	v_pk_fma_f32 v[46:47], v[18:19], v[60:61], v[46:47]
	v_and_b32_e32 v59, 0xffff0000, v36
	v_pk_mul_f32 v[64:65], v[46:47], v[46:47]
	v_pk_fma_f32 v[54:55], v[10:11], v[60:61], v[54:55]
	v_fmamk_f32 v58, v64, 0xbdd2d3e8, v178
	v_fmamk_f32 v63, v65, 0xbdd2d3e8, v178
	v_mul_f32_e32 v58, v46, v58
	v_mul_f32_e32 v63, v47, v63
	v_exp_f32_e32 v58, v58
	v_exp_f32_e32 v63, v63
	v_add_f32_e32 v58, 1.0, v58
	v_add_f32_e32 v63, 1.0, v63
	v_rcp_f32_e32 v64, v58
	v_rcp_f32_e32 v65, v63
	v_lshlrev_b32_e32 v58, 16, v36
	v_pk_fma_f32 v[56:57], v[22:23], v[58:59], v[56:57]
	v_pk_fma_f32 v[52:53], v[14:15], v[58:59], v[52:53]
	v_pk_mul_f32 v[46:47], v[46:47], v[64:65]
	s_nop 0
	v_pk_mul_f32 v[46:47], v[56:57], v[46:47]
	v_lshlrev_b32_e32 v56, 16, v35
	v_and_b32_e32 v57, 0xffff0000, v35
	v_pk_fma_f32 v[38:39], v[20:21], v[56:57], v[38:39]
	v_cvt_pk_bf16_f32 v64, v46, v47
	v_pk_mul_f32 v[66:67], v[38:39], v[38:39]
	v_and_b32_e32 v47, 0xffff0000, v37
	v_fmamk_f32 v46, v66, 0xbdd2d3e8, v178
	v_fmamk_f32 v63, v67, 0xbdd2d3e8, v178
	v_mul_f32_e32 v46, v38, v46
	v_mul_f32_e32 v63, v39, v63
	v_exp_f32_e32 v46, v46
	v_exp_f32_e32 v63, v63
	v_pk_fma_f32 v[50:51], v[12:13], v[56:57], v[50:51]
	v_add_f32_e32 v46, 1.0, v46
	v_add_f32_e32 v63, 1.0, v63
	v_rcp_f32_e32 v66, v46
	v_rcp_f32_e32 v67, v63
	v_lshlrev_b32_e32 v46, 16, v37
	v_pk_fma_f32 v[40:41], v[24:25], v[46:47], v[40:41]
	v_pk_fma_f32 v[46:47], v[16:17], v[46:47], v[48:49]
	v_pk_mul_f32 v[38:39], v[38:39], v[66:67]
	s_nop 0
	v_pk_mul_f32 v[38:39], v[40:41], v[38:39]
	s_nop 0
	v_cvt_pk_bf16_f32 v65, v38, v39
	v_add_co_u32_e32 v38, vcc, s8, v44
	s_nop 1
	v_addc_co_u32_e32 v39, vcc, 0, v45, vcc
	global_store_dwordx2 v[38:39], v[64:65], off offset:3072
	ds_read2_b64 v[38:41], v62 offset0:198 offset1:230
	v_add_co_u32_e32 v44, vcc, s37, v44
	v_add_u32_e32 v62, 0x840, v62
	s_nop 0
	v_addc_co_u32_e32 v45, vcc, 0, v45, vcc
	s_waitcnt lgkmcnt(0)
	v_lshlrev_b32_e32 v64, 16, v38
	v_and_b32_e32 v65, 0xffff0000, v38
	v_pk_fma_f32 v[54:55], v[18:19], v[64:65], v[54:55]
	v_lshlrev_b32_e32 v64, 16, v40
	v_pk_mul_f32 v[60:61], v[54:55], v[54:55]
	v_and_b32_e32 v65, 0xffff0000, v40
	v_fmamk_f32 v60, v60, 0xbdd2d3e8, v178
	v_fmamk_f32 v58, v61, 0xbdd2d3e8, v178
	v_mul_f32_e32 v60, v54, v60
	v_mul_f32_e32 v58, v55, v58
	v_exp_f32_e32 v60, v60
	v_exp_f32_e32 v58, v58
	v_pk_fma_f32 v[52:53], v[22:23], v[64:65], v[52:53]
	v_lshlrev_b32_e32 v56, 16, v41
	v_add_f32_e32 v60, 1.0, v60
	v_add_f32_e32 v58, 1.0, v58
	v_rcp_f32_e32 v60, v60
	v_rcp_f32_e32 v61, v58
	v_and_b32_e32 v57, 0xffff0000, v41
	v_pk_fma_f32 v[46:47], v[24:25], v[56:57], v[46:47]
	v_pk_mul_f32 v[54:55], v[54:55], v[60:61]
	s_nop 0
	v_pk_mul_f32 v[52:53], v[52:53], v[54:55]
	v_lshlrev_b32_e32 v54, 16, v39
	v_and_b32_e32 v55, 0xffff0000, v39
	v_pk_fma_f32 v[50:51], v[20:21], v[54:55], v[50:51]
	v_cvt_pk_bf16_f32 v52, v52, v53
	v_pk_mul_f32 v[54:55], v[50:51], v[50:51]
	s_nop 0
	v_fmamk_f32 v53, v54, 0xbdd2d3e8, v178
	v_fmamk_f32 v48, v55, 0xbdd2d3e8, v178
	v_mul_f32_e32 v53, v50, v53
	v_mul_f32_e32 v48, v51, v48
	v_exp_f32_e32 v53, v53
	v_exp_f32_e32 v48, v48
	v_add_f32_e32 v53, 1.0, v53
	v_add_f32_e32 v48, 1.0, v48
	v_rcp_f32_e32 v54, v53
	v_rcp_f32_e32 v55, v48
	s_nop 0
	v_pk_mul_f32 v[48:49], v[50:51], v[54:55]
	s_nop 0
	v_pk_mul_f32 v[46:47], v[46:47], v[48:49]
	s_nop 0
	v_cvt_pk_bf16_f32 v53, v46, v47
	global_store_dwordx2 v[44:45], v[52:53], off offset:512
	s_cbranch_scc0 .LBB0_42
	s_add_i32 s16, s99, s16
	s_cmpk_gt_i32 s16, 0xaff
	s_cbranch_scc0 .LBB0_32

.LBB0_51:
	v_mov_b32_e32 v2, v176
	s_lshl_b32 s4, s30, 7
	s_and_b32 s5, s30, 1
	v_lshlrev_b32_e32 v3, 4, v2
	v_and_b32_e32 v4, 32, v2
	v_bfe_i32 v5, v2, 3, 25
	v_bfe_u32 v6, v2, 2, 26
	s_and_b32 s4, s4, 0xffffff00
	v_bfi_b32 v5, -16, v5, v6
	v_bitop3_b32 v3, v3, v4, 48 bitop3:0x6c
	s_lshl_b32 s29, s5, 10
	v_and_or_b32 v3, v2, 64, v3
	v_add_u32_e32 v4, s4, v5
	s_add_u32 s8, s15, s29
	v_lshl_or_b32 v130, v4, 11, v3
	v_readfirstlane_b32 s6, v2
	v_or_b32_e32 v4, 0x1ffffe, v6
	v_lshlrev_b32_e32 v6, 7, v5
	s_addc_u32 s9, s16, 0
	s_lshl_b32 s6, s6, 4
	v_and_b32_e32 v7, 0x1fff00, v6
	s_and_b32 s41, s6, 0xfffffc00
	v_add_lshl_u32 v7, v7, v4, 11
	v_cmp_lt_i32_e32 vcc, 1, v5
	s_cmp_lg_u32 0, -1
	s_cselect_b32 s6, 0, 0
	v_cndmask_b32_e32 v7, 0, v7, vcc
	v_or_b32_e32 v131, v7, v3
	v_add_u32_e32 v7, 0x2000, v6
	s_add_i32 s41, s41, s6
	v_and_b32_e32 v7, 0x1fff00, v7
	s_movk_i32 s43, 0xffc1
	s_add_u32 s6, s12, s29
	v_add_lshl_u32 v7, v7, v4, 11
	v_cmp_lt_i32_e32 vcc, s43, v5
	s_barrier
	s_addc_u32 s7, s13, 0
	s_mov_b32 m0, s41
	global_load_lds_dwordx4 v131, s[6:7]
	v_cndmask_b32_e32 v7, 0, v7, vcc
	s_add_i32 s42, s41, 0x8000
	s_mov_b32 m0, s42
	global_load_lds_dwordx4 v130, s[8:9]
	s_add_i32 s39, s41, 0x2000
	v_or_b32_e32 v135, v7, v3
	v_add_u32_e32 v7, 0x4000, v6
	s_mov_b32 m0, s39
	global_load_lds_dwordx4 v135, s[6:7]
	s_add_i32 s39, s41, 0xa000
	v_and_b32_e32 v7, 0x1fff00, v7
	s_movk_i32 s43, 0xff81
	s_add_u32 s46, s8, 0x20000
	v_add_lshl_u32 v7, v7, v4, 11
	v_cmp_lt_i32_e32 vcc, s43, v5
	s_addc_u32 s47, s9, 0
	s_mov_b32 m0, s39
	global_load_lds_dwordx4 v130, s[46:47]
	s_add_i32 s39, s41, 0x4000
	v_cndmask_b32_e32 v7, 0, v7, vcc
	v_add_u32_e32 v6, 0x6000, v6
	v_or_b32_e32 v136, v7, v3
	s_mov_b32 m0, s39
	global_load_lds_dwordx4 v136, s[6:7]
	s_add_i32 s39, s41, 0xc000
	v_and_b32_e32 v6, 0x1fff00, v6
	s_movk_i32 s43, 0xff41
	s_add_u32 s46, s8, 0x40000
	v_add_lshl_u32 v4, v6, v4, 11
	v_cmp_lt_i32_e32 vcc, s43, v5
	s_addc_u32 s47, s9, 0
	s_mov_b32 m0, s39
	global_load_lds_dwordx4 v130, s[46:47]
	s_add_i32 s39, s41, 0x6000
	v_cndmask_b32_e32 v4, 0, v4, vcc
	v_or_b32_e32 v137, v4, v3
	s_mov_b32 m0, s39
	global_load_lds_dwordx4 v137, s[6:7]
	s_add_i32 s39, s41, 0xe000
	s_add_u32 s6, s8, 0x60000
	v_and_b32_e32 v3, 15, v2
	v_lshlrev_b32_e32 v5, 2, v2
	s_addc_u32 s7, s9, 0
	v_and_b32_e32 v4, 48, v2
	v_lshlrev_b32_e32 v3, 6, v3
	v_and_b32_e32 v5, 32, v5
	s_mov_b32 m0, s39
	global_load_lds_dwordx4 v130, s[6:7]
	v_bitop3_b32 v138, v3, v5, v4 bitop3:0x36
	v_lshlrev_b32_e32 v3, 7, v2
	v_lshlrev_b32_e32 v2, 6, v2
	s_add_u32 s6, s19, s29
	v_and_b32_e32 v140, 0xffffc000, v2
	v_and_b32_e32 v2, 0x3c0, v2
	s_addc_u32 s7, s25, 0
	v_bitop3_b32 v142, v2, v5, v4 bitop3:0x36
	s_add_u32 s8, s8, 0x80
	v_mov_b32_e32 v2, 0
	s_mov_b32 s40, 0
	v_and_b32_e32 v139, 0x6000, v3
	v_or_b32_e32 v141, 0x800, v140
	v_or_b32_e32 v143, 0x1000, v140
	v_or_b32_e32 v144, 0x1800, v140
	v_or_b32_e32 v145, 0x2000, v140
	v_or_b32_e32 v146, 0x2800, v140
	v_or_b32_e32 v147, 0x3000, v140
	v_or_b32_e32 v148, 0x3800, v140
	s_addc_u32 s9, s9, 0
	v_mov_b32_e32 v3, v2
	v_mov_b32_e32 v4, v2
	v_mov_b32_e32 v5, v2
	v_mov_b32_e32 v6, v2
	v_mov_b32_e32 v7, v2
	v_mov_b32_e32 v8, v2
	v_mov_b32_e32 v9, v2
	v_mov_b32_e32 v10, v2
	v_mov_b32_e32 v11, v2
	v_mov_b32_e32 v12, v2
	v_mov_b32_e32 v13, v2
	v_mov_b32_e32 v14, v2
	v_mov_b32_e32 v15, v2
	v_mov_b32_e32 v16, v2
	v_mov_b32_e32 v17, v2
	v_mov_b32_e32 v18, v2
	v_mov_b32_e32 v19, v2
	v_mov_b32_e32 v20, v2
	v_mov_b32_e32 v21, v2
	v_mov_b32_e32 v22, v2
	v_mov_b32_e32 v23, v2
	v_mov_b32_e32 v24, v2
	v_mov_b32_e32 v25, v2
	v_mov_b32_e32 v26, v2
	v_mov_b32_e32 v27, v2
	v_mov_b32_e32 v28, v2
	v_mov_b32_e32 v29, v2
	v_mov_b32_e32 v30, v2
	v_mov_b32_e32 v31, v2
	v_mov_b32_e32 v32, v2
	v_mov_b32_e32 v33, v2
	v_mov_b32_e32 v34, v2
	v_mov_b32_e32 v35, v2
	v_mov_b32_e32 v36, v2
	v_mov_b32_e32 v37, v2
	v_mov_b32_e32 v38, v2
	v_mov_b32_e32 v39, v2
	v_mov_b32_e32 v40, v2
	v_mov_b32_e32 v41, v2
	v_mov_b32_e32 v42, v2
	v_mov_b32_e32 v43, v2
	v_mov_b32_e32 v44, v2
	v_mov_b32_e32 v45, v2
	v_mov_b32_e32 v46, v2
	v_mov_b32_e32 v47, v2
	v_mov_b32_e32 v48, v2
	v_mov_b32_e32 v49, v2
	v_mov_b32_e32 v50, v2
	v_mov_b32_e32 v51, v2
	v_mov_b32_e32 v52, v2
	v_mov_b32_e32 v53, v2
	v_mov_b32_e32 v54, v2
	v_mov_b32_e32 v55, v2
	v_mov_b32_e32 v56, v2
	v_mov_b32_e32 v57, v2
	v_mov_b32_e32 v58, v2
	v_mov_b32_e32 v59, v2
	v_mov_b32_e32 v60, v2
	v_mov_b32_e32 v61, v2
	v_mov_b32_e32 v62, v2
	v_mov_b32_e32 v63, v2
	v_mov_b32_e32 v64, v2
	v_mov_b32_e32 v65, v2
	v_mov_b32_e32 v66, v2
	v_mov_b32_e32 v67, v2
	v_mov_b32_e32 v68, v2
	v_mov_b32_e32 v69, v2
	v_mov_b32_e32 v70, v2
	v_mov_b32_e32 v71, v2
	v_mov_b32_e32 v72, v2
	v_mov_b32_e32 v73, v2
	v_mov_b32_e32 v74, v2
	v_mov_b32_e32 v75, v2
	v_mov_b32_e32 v76, v2
	v_mov_b32_e32 v77, v2
	v_mov_b32_e32 v78, v2
	v_mov_b32_e32 v79, v2
	v_mov_b32_e32 v80, v2
	v_mov_b32_e32 v81, v2
	v_mov_b32_e32 v82, v2
	v_mov_b32_e32 v83, v2
	v_mov_b32_e32 v84, v2
	v_mov_b32_e32 v85, v2
	v_mov_b32_e32 v86, v2
	v_mov_b32_e32 v87, v2
	v_mov_b32_e32 v88, v2
	v_mov_b32_e32 v89, v2
	v_mov_b32_e32 v90, v2
	v_mov_b32_e32 v91, v2
	v_mov_b32_e32 v92, v2
	v_mov_b32_e32 v93, v2
	v_mov_b32_e32 v94, v2
	v_mov_b32_e32 v95, v2
	v_mov_b32_e32 v96, v2
	v_mov_b32_e32 v97, v2
	v_mov_b32_e32 v98, v2
	v_mov_b32_e32 v99, v2
	v_mov_b32_e32 v100, v2
	v_mov_b32_e32 v101, v2
	v_mov_b32_e32 v102, v2
	v_mov_b32_e32 v103, v2
	v_mov_b32_e32 v104, v2
	v_mov_b32_e32 v105, v2
	v_mov_b32_e32 v106, v2
	v_mov_b32_e32 v107, v2
	v_mov_b32_e32 v108, v2
	v_mov_b32_e32 v109, v2
	v_mov_b32_e32 v110, v2
	v_mov_b32_e32 v111, v2
	v_mov_b32_e32 v112, v2
	v_mov_b32_e32 v113, v2
	v_mov_b32_e32 v114, v2
	v_mov_b32_e32 v115, v2
	v_mov_b32_e32 v116, v2
	v_mov_b32_e32 v117, v2
	v_mov_b32_e32 v118, v2
	v_mov_b32_e32 v119, v2
	v_mov_b32_e32 v120, v2
	v_mov_b32_e32 v121, v2
	v_mov_b32_e32 v122, v2
	v_mov_b32_e32 v123, v2
	v_mov_b32_e32 v124, v2
	v_mov_b32_e32 v125, v2
	v_mov_b32_e32 v126, v2
	v_mov_b32_e32 v127, v2
	v_mov_b32_e32 v128, v2
	v_mov_b32_e32 v129, v2
	s_waitcnt vmcnt(0)
	s_barrier
	s_branch .LBB0_53

.LBB0_58:
	s_lshl_b32 s10, s25, 6
	s_and_b32 s10, s10, 0x1c0
	s_ashr_i32 s11, s25, 3
	s_add_i32 s10, s10, s11
	s_ashr_i32 s12, s10, 31
	s_lshr_b32 s12, s12, 27
	s_add_i32 s12, s10, s12
	s_ashr_i32 s12, s12, 5
	s_lshl_b32 s13, s12, 11
	s_lshl_b32 s12, s12, 10
	s_lshl_b32 s10, s10, 5
	v_mov_b32_e32 v2, v176
	s_lshl_b32 s11, s11, 8
	s_sub_i32 s10, s10, s12
	s_and_b32 s11, s11, 0x700
	v_readfirstlane_b32 s12, v2
	v_lshlrev_b32_e32 v3, 4, v2
	v_and_b32_e32 v4, 32, v2
	v_bfe_i32 v5, v2, 3, 25
	v_lshrrev_b32_e32 v6, 2, v2
	s_lshl_b32 s12, s12, 4
	s_or_b32 s11, s13, s11
	s_and_b32 s10, s10, 0xffffff00
	v_bfi_b32 v5, -16, v5, v6
	v_bitop3_b32 v3, v3, v4, 48 bitop3:0x6c
	s_and_b32 s42, s12, 0xfffffc00
	v_and_or_b32 v3, v2, 64, v3
	v_add_u32_e32 v4, s10, v5
	s_cmp_lg_u32 0, -1
	v_lshl_or_b32 v133, v4, 9, v3
	v_add_u32_e32 v4, s11, v5
	s_cselect_b32 s12, 0, 0
	s_add_i32 s42, s42, s12
	s_barrier
	v_lshl_or_b32 v134, v4, 9, v3
	s_mov_b32 m0, s42
	global_load_lds_dwordx4 v134, s[2:3]
	s_add_i32 s43, s42, 0x8000
	s_mov_b32 m0, s43
	global_load_lds_dwordx4 v133, s[4:5]
	s_add_i32 s12, s42, 0x2000
	s_add_i32 s16, s42, 0xa000
	v_add_u32_e32 v135, 0x8000, v134
	s_mov_b32 m0, s12
	global_load_lds_dwordx4 v135, s[2:3]
	s_add_u32 s12, s4, 0x8000
	s_addc_u32 s13, s5, 0
	s_mov_b32 m0, s16
	global_load_lds_dwordx4 v133, s[12:13]
	s_add_i32 s12, s42, 0x4000
	s_add_i32 s16, s42, 0xc000
	v_add_u32_e32 v136, 0x10000, v134
	s_mov_b32 m0, s12
	global_load_lds_dwordx4 v136, s[2:3]
	s_add_u32 s12, s4, 0x10000
	s_addc_u32 s13, s5, 0
	s_mov_b32 m0, s16
	global_load_lds_dwordx4 v133, s[12:13]
	s_add_i32 s12, s42, 0x6000
	s_add_i32 s16, s42, 0xe000
	v_and_b32_e32 v3, 15, v2
	v_lshlrev_b32_e32 v5, 2, v2
	v_add_u32_e32 v137, 0x18000, v134
	s_mov_b32 m0, s12
	global_load_lds_dwordx4 v137, s[2:3]
	s_add_u32 s12, s4, 0x18000
	v_and_b32_e32 v4, 48, v2
	v_lshlrev_b32_e32 v3, 6, v3
	v_and_b32_e32 v5, 32, v5
	s_addc_u32 s13, s5, 0
	s_mov_b32 m0, s16
	global_load_lds_dwordx4 v133, s[12:13]
	v_bitop3_b32 v138, v3, v5, v4 bitop3:0x36
	v_lshlrev_b32_e32 v3, 7, v2
	v_lshlrev_b32_e32 v2, 6, v2
	v_and_b32_e32 v140, 0xffffc000, v2
	v_and_b32_e32 v2, 0x3c0, v2
	v_bitop3_b32 v142, v2, v5, v4 bitop3:0x36
	v_mov_b32_e32 v2, 0
	s_mov_b32 s41, 0
	v_and_b32_e32 v139, 0x6000, v3
	v_or_b32_e32 v141, 0x800, v140
	v_or_b32_e32 v143, 0x1000, v140
	v_or_b32_e32 v144, 0x1800, v140
	v_or_b32_e32 v145, 0x2000, v140
	v_or_b32_e32 v146, 0x2800, v140
	v_or_b32_e32 v147, 0x3000, v140
	v_or_b32_e32 v148, 0x3800, v140
	s_mov_b64 s[12:13], s[8:9]
	s_mov_b64 s[16:17], s[6:7]
	v_mov_b32_e32 v3, v2
	v_mov_b32_e32 v4, v2
	v_mov_b32_e32 v5, v2
	v_mov_b32_e32 v6, v2
	v_mov_b32_e32 v7, v2
	v_mov_b32_e32 v8, v2
	v_mov_b32_e32 v9, v2
	v_mov_b32_e32 v10, v2
	v_mov_b32_e32 v11, v2
	v_mov_b32_e32 v12, v2
	v_mov_b32_e32 v13, v2
	v_mov_b32_e32 v14, v2
	v_mov_b32_e32 v15, v2
	v_mov_b32_e32 v16, v2
	v_mov_b32_e32 v17, v2
	v_mov_b32_e32 v18, v2
	v_mov_b32_e32 v19, v2
	v_mov_b32_e32 v20, v2
	v_mov_b32_e32 v21, v2
	v_mov_b32_e32 v22, v2
	v_mov_b32_e32 v23, v2
	v_mov_b32_e32 v24, v2
	v_mov_b32_e32 v25, v2
	v_mov_b32_e32 v26, v2
	v_mov_b32_e32 v27, v2
	v_mov_b32_e32 v28, v2
	v_mov_b32_e32 v29, v2
	v_mov_b32_e32 v30, v2
	v_mov_b32_e32 v31, v2
	v_mov_b32_e32 v32, v2
	v_mov_b32_e32 v33, v2
	v_mov_b32_e32 v34, v2
	v_mov_b32_e32 v35, v2
	v_mov_b32_e32 v36, v2
	v_mov_b32_e32 v37, v2
	v_mov_b32_e32 v38, v2
	v_mov_b32_e32 v39, v2
	v_mov_b32_e32 v40, v2
	v_mov_b32_e32 v41, v2
	v_mov_b32_e32 v42, v2
	v_mov_b32_e32 v43, v2
	v_mov_b32_e32 v44, v2
	v_mov_b32_e32 v45, v2
	v_mov_b32_e32 v46, v2
	v_mov_b32_e32 v47, v2
	v_mov_b32_e32 v48, v2
	v_mov_b32_e32 v49, v2
	v_mov_b32_e32 v50, v2
	v_mov_b32_e32 v51, v2
	v_mov_b32_e32 v52, v2
	v_mov_b32_e32 v53, v2
	v_mov_b32_e32 v54, v2
	v_mov_b32_e32 v55, v2
	v_mov_b32_e32 v56, v2
	v_mov_b32_e32 v57, v2
	v_mov_b32_e32 v58, v2
	v_mov_b32_e32 v59, v2
	v_mov_b32_e32 v60, v2
	v_mov_b32_e32 v61, v2
	v_mov_b32_e32 v62, v2
	v_mov_b32_e32 v63, v2
	v_mov_b32_e32 v64, v2
	v_mov_b32_e32 v65, v2
	v_mov_b32_e32 v66, v2
	v_mov_b32_e32 v67, v2
	v_mov_b32_e32 v68, v2
	v_mov_b32_e32 v69, v2
	v_mov_b32_e32 v70, v2
	v_mov_b32_e32 v71, v2
	v_mov_b32_e32 v72, v2
	v_mov_b32_e32 v73, v2
	v_mov_b32_e32 v74, v2
	v_mov_b32_e32 v75, v2
	v_mov_b32_e32 v76, v2
	v_mov_b32_e32 v77, v2
	v_mov_b32_e32 v78, v2
	v_mov_b32_e32 v79, v2
	v_mov_b32_e32 v80, v2
	v_mov_b32_e32 v81, v2
	v_mov_b32_e32 v82, v2
	v_mov_b32_e32 v83, v2
	v_mov_b32_e32 v84, v2
	v_mov_b32_e32 v85, v2
	v_mov_b32_e32 v86, v2
	v_mov_b32_e32 v87, v2
	v_mov_b32_e32 v88, v2
	v_mov_b32_e32 v89, v2
	v_mov_b32_e32 v90, v2
	v_mov_b32_e32 v91, v2
	v_mov_b32_e32 v92, v2
	v_mov_b32_e32 v93, v2
	v_mov_b32_e32 v94, v2
	v_mov_b32_e32 v95, v2
	v_mov_b32_e32 v96, v2
	v_mov_b32_e32 v97, v2
	v_mov_b32_e32 v98, v2
	v_mov_b32_e32 v99, v2
	v_mov_b32_e32 v100, v2
	v_mov_b32_e32 v101, v2
	v_mov_b32_e32 v102, v2
	v_mov_b32_e32 v103, v2
	v_mov_b32_e32 v104, v2
	v_mov_b32_e32 v105, v2
	v_mov_b32_e32 v106, v2
	v_mov_b32_e32 v107, v2
	v_mov_b32_e32 v108, v2
	v_mov_b32_e32 v109, v2
	v_mov_b32_e32 v110, v2
	v_mov_b32_e32 v111, v2
	v_mov_b32_e32 v112, v2
	v_mov_b32_e32 v113, v2
	v_mov_b32_e32 v114, v2
	v_mov_b32_e32 v115, v2
	v_mov_b32_e32 v116, v2
	v_mov_b32_e32 v117, v2
	v_mov_b32_e32 v118, v2
	v_mov_b32_e32 v119, v2
	v_mov_b32_e32 v120, v2
	v_mov_b32_e32 v121, v2
	v_mov_b32_e32 v122, v2
	v_mov_b32_e32 v123, v2
	v_mov_b32_e32 v124, v2
	v_mov_b32_e32 v125, v2
	v_mov_b32_e32 v126, v2
	v_mov_b32_e32 v127, v2
	v_mov_b32_e32 v128, v2
	v_mov_b32_e32 v129, v2
	s_waitcnt vmcnt(0)
	s_barrier
	s_branch .LBB0_60

.LBB0_70:
	s_lshl_b32 s16, s15, 7
	s_and_b32 s16, s16, 0x380
	s_ashr_i32 s17, s15, 3
	s_add_i32 s16, s16, s17
	s_ashr_i32 s18, s16, 31
	s_lshr_b32 s18, s18, 26
	s_add_i32 s18, s16, s18
	s_lshl_b32 s18, s18, 5
	s_and_b32 s18, s18, 0xfffff800
	s_lshl_b32 s16, s16, 5
	s_sub_i32 s16, s16, s18
	v_mov_b32_e32 v2, v176
	s_lshl_b32 s17, s17, 8
	s_and_b32 s30, s16, 0xffffff00
	s_and_b32 s17, s17, 0x700
	v_readfirstlane_b32 s16, v2
	v_lshlrev_b32_e32 v3, 4, v2
	v_and_b32_e32 v4, 32, v2
	v_bfe_i32 v5, v2, 3, 25
	v_lshrrev_b32_e32 v6, 2, v2
	s_lshl_b32 s16, s16, 4
	s_or_b32 s25, s18, s17
	v_bfi_b32 v5, -16, v5, v6
	v_bitop3_b32 v3, v3, v4, 48 bitop3:0x6c
	s_and_b32 s41, s16, 0xfffffc00
	v_and_or_b32 v3, v2, 64, v3
	v_add_u32_e32 v4, s30, v5
	s_cmp_lg_u32 0, -1
	v_lshl_or_b32 v130, v4, 11, v3
	v_add_u32_e32 v4, s25, v5
	s_cselect_b32 s16, 0, 0
	s_add_i32 s41, s41, s16
	s_barrier
	v_lshl_or_b32 v131, v4, 11, v3
	s_mov_b32 m0, s41
	global_load_lds_dwordx4 v131, s[2:3]
	s_add_i32 s42, s41, 0x8000
	s_mov_b32 m0, s42
	global_load_lds_dwordx4 v130, s[4:5]
	s_add_i32 s16, s41, 0x2000
	s_add_i32 s18, s41, 0xa000
	v_add_u32_e32 v132, 0x20000, v131
	s_mov_b32 m0, s16
	global_load_lds_dwordx4 v132, s[2:3]
	s_add_u32 s16, s4, 0x20000
	s_addc_u32 s17, s5, 0
	s_mov_b32 m0, s18
	global_load_lds_dwordx4 v130, s[16:17]
	s_add_i32 s16, s41, 0x4000
	s_add_i32 s18, s41, 0xc000
	v_add_u32_e32 v133, 0x40000, v131
	s_mov_b32 m0, s16
	global_load_lds_dwordx4 v133, s[2:3]
	s_add_u32 s16, s4, 0x40000
	s_addc_u32 s17, s5, 0
	s_mov_b32 m0, s18
	global_load_lds_dwordx4 v130, s[16:17]
	s_add_i32 s16, s41, 0x6000
	s_add_i32 s18, s41, 0xe000
	v_add_u32_e32 v134, 0x60000, v131
	s_mov_b32 m0, s16
	global_load_lds_dwordx4 v134, s[2:3]
	s_add_u32 s16, s4, 0x60000
	v_and_b32_e32 v3, 15, v2
	v_lshlrev_b32_e32 v5, 2, v2
	s_addc_u32 s17, s5, 0
	s_mov_b32 m0, s18
	global_load_lds_dwordx4 v130, s[16:17]
	v_and_b32_e32 v4, 48, v2
	v_lshlrev_b32_e32 v3, 6, v3
	v_and_b32_e32 v5, 32, v5
	v_bitop3_b32 v135, v3, v5, v4 bitop3:0x36
	v_lshlrev_b32_e32 v3, 7, v2
	v_lshlrev_b32_e32 v2, 6, v2
	v_and_b32_e32 v137, 0xffffc000, v2
	v_and_b32_e32 v2, 0x3c0, v2
	v_mov_b32_e32 v10, 0
	s_mov_b32 s40, 0
	v_and_b32_e32 v136, 0x6000, v3
	v_or_b32_e32 v138, 0x800, v137
	v_bitop3_b32 v139, v2, v5, v4 bitop3:0x36
	v_or_b32_e32 v140, 0x1000, v137
	v_or_b32_e32 v141, 0x1800, v137
	v_or_b32_e32 v146, 0x2000, v137
	v_or_b32_e32 v147, 0x2800, v137
	v_or_b32_e32 v148, 0x3000, v137
	v_or_b32_e32 v149, 0x3800, v137
	s_mov_b64 s[16:17], s[12:13]
	s_mov_b64 s[18:19], s[10:11]
	v_mov_b32_e32 v11, v10
	v_mov_b32_e32 v12, v10
	v_mov_b32_e32 v13, v10
	v_mov_b32_e32 v2, v10
	v_mov_b32_e32 v3, v10
	v_mov_b32_e32 v4, v10
	v_mov_b32_e32 v5, v10
	v_mov_b32_e32 v14, v10
	v_mov_b32_e32 v15, v10
	v_mov_b32_e32 v16, v10
	v_mov_b32_e32 v17, v10
	v_mov_b32_e32 v6, v10
	v_mov_b32_e32 v7, v10
	v_mov_b32_e32 v8, v10
	v_mov_b32_e32 v9, v10
	v_mov_b32_e32 v26, v10
	v_mov_b32_e32 v27, v10
	v_mov_b32_e32 v28, v10
	v_mov_b32_e32 v29, v10
	v_mov_b32_e32 v18, v10
	v_mov_b32_e32 v19, v10
	v_mov_b32_e32 v20, v10
	v_mov_b32_e32 v21, v10
	v_mov_b32_e32 v30, v10
	v_mov_b32_e32 v31, v10
	v_mov_b32_e32 v32, v10
	v_mov_b32_e32 v33, v10
	v_mov_b32_e32 v22, v10
	v_mov_b32_e32 v23, v10
	v_mov_b32_e32 v24, v10
	v_mov_b32_e32 v25, v10
	v_mov_b32_e32 v42, v10
	v_mov_b32_e32 v43, v10
	v_mov_b32_e32 v44, v10
	v_mov_b32_e32 v45, v10
	v_mov_b32_e32 v34, v10
	v_mov_b32_e32 v35, v10
	v_mov_b32_e32 v36, v10
	v_mov_b32_e32 v37, v10
	v_mov_b32_e32 v46, v10
	v_mov_b32_e32 v47, v10
	v_mov_b32_e32 v48, v10
	v_mov_b32_e32 v49, v10
	v_mov_b32_e32 v38, v10
	v_mov_b32_e32 v39, v10
	v_mov_b32_e32 v40, v10
	v_mov_b32_e32 v41, v10
	v_mov_b32_e32 v58, v10
	v_mov_b32_e32 v59, v10
	v_mov_b32_e32 v60, v10
	v_mov_b32_e32 v61, v10
	v_mov_b32_e32 v50, v10
	v_mov_b32_e32 v51, v10
	v_mov_b32_e32 v52, v10
	v_mov_b32_e32 v53, v10
	v_mov_b32_e32 v62, v10
	v_mov_b32_e32 v63, v10
	v_mov_b32_e32 v64, v10
	v_mov_b32_e32 v65, v10
	v_mov_b32_e32 v54, v10
	v_mov_b32_e32 v55, v10
	v_mov_b32_e32 v56, v10
	v_mov_b32_e32 v57, v10
	v_mov_b32_e32 v74, v10
	v_mov_b32_e32 v75, v10
	v_mov_b32_e32 v76, v10
	v_mov_b32_e32 v77, v10
	v_mov_b32_e32 v66, v10
	v_mov_b32_e32 v67, v10
	v_mov_b32_e32 v68, v10
	v_mov_b32_e32 v69, v10
	v_mov_b32_e32 v78, v10
	v_mov_b32_e32 v79, v10
	v_mov_b32_e32 v80, v10
	v_mov_b32_e32 v81, v10
	v_mov_b32_e32 v70, v10
	v_mov_b32_e32 v71, v10
	v_mov_b32_e32 v72, v10
	v_mov_b32_e32 v73, v10
	v_mov_b32_e32 v90, v10
	v_mov_b32_e32 v91, v10
	v_mov_b32_e32 v92, v10
	v_mov_b32_e32 v93, v10
	v_mov_b32_e32 v82, v10
	v_mov_b32_e32 v83, v10
	v_mov_b32_e32 v84, v10
	v_mov_b32_e32 v85, v10
	v_mov_b32_e32 v94, v10
	v_mov_b32_e32 v95, v10
	v_mov_b32_e32 v96, v10
	v_mov_b32_e32 v97, v10
	v_mov_b32_e32 v86, v10
	v_mov_b32_e32 v87, v10
	v_mov_b32_e32 v88, v10
	v_mov_b32_e32 v89, v10
	v_mov_b32_e32 v102, v10
	v_mov_b32_e32 v103, v10
	v_mov_b32_e32 v104, v10
	v_mov_b32_e32 v105, v10
	v_mov_b32_e32 v98, v10
	v_mov_b32_e32 v99, v10
	v_mov_b32_e32 v100, v10
	v_mov_b32_e32 v101, v10
	v_mov_b32_e32 v110, v10
	v_mov_b32_e32 v111, v10
	v_mov_b32_e32 v112, v10
	v_mov_b32_e32 v113, v10
	v_mov_b32_e32 v106, v10
	v_mov_b32_e32 v107, v10
	v_mov_b32_e32 v108, v10
	v_mov_b32_e32 v109, v10
	v_mov_b32_e32 v118, v10
	v_mov_b32_e32 v119, v10
	v_mov_b32_e32 v120, v10
	v_mov_b32_e32 v121, v10
	v_mov_b32_e32 v114, v10
	v_mov_b32_e32 v115, v10
	v_mov_b32_e32 v116, v10
	v_mov_b32_e32 v117, v10
	v_mov_b32_e32 v126, v10
	v_mov_b32_e32 v127, v10
	v_mov_b32_e32 v128, v10
	v_mov_b32_e32 v129, v10
	v_mov_b32_e32 v122, v10
	v_mov_b32_e32 v123, v10
	v_mov_b32_e32 v124, v10
	v_mov_b32_e32 v125, v10
	s_waitcnt vmcnt(0)
	s_barrier
	s_branch .LBB0_72

.LBB0_105:
	s_ashr_i32 s4, s65, 3
	s_lshl_b32 s2, s65, 8
	s_ashr_i32 s5, s4, 31
	s_and_b32 s15, s2, 0x700
	s_lshl_b64 s[2:3], s[4:5], 20
	s_add_u32 s2, s16, s2
	s_addc_u32 s3, s17, s3
	s_lshl_b64 s[6:7], s[4:5], 16
	v_mov_b32_e32 v2, v176
	s_add_u32 s6, s18, s6
	s_addc_u32 s7, s19, s7
	v_readfirstlane_b32 s8, v2
	s_lshl_b32 s8, s8, 4
	v_lshlrev_b32_e32 v3, 4, v2
	v_and_b32_e32 v4, 32, v2
	v_bfe_i32 v5, v2, 3, 25
	v_lshrrev_b32_e32 v6, 2, v2
	s_and_b32 s66, s8, 0xfffffc00
	v_bfi_b32 v5, -16, v5, v6
	v_bitop3_b32 v3, v3, v4, 48 bitop3:0x6c
	s_cmp_lg_u32 0, -1
	v_and_or_b32 v3, v2, 64, v3
	v_add_u32_e32 v4, s15, v5
	s_cselect_b32 s8, 0, 0
	s_add_i32 s66, s66, s8
	s_barrier
	v_lshl_or_b32 v131, v4, 9, v3
	s_mov_b32 m0, s66
	global_load_lds_dwordx4 v131, s[2:3]
	v_lshl_or_b32 v130, v5, 9, v3
	s_add_i32 s67, s66, 0x8000
	s_mov_b32 m0, s67
	global_load_lds_dwordx4 v130, s[6:7]
	s_add_i32 s8, s66, 0x2000
	s_add_i32 s10, s66, 0xa000
	v_add_u32_e32 v132, 0x8000, v131
	s_mov_b32 m0, s8
	global_load_lds_dwordx4 v132, s[2:3]
	s_add_u32 s8, s6, 0x8000
	s_addc_u32 s9, s7, 0
	s_mov_b32 m0, s10
	global_load_lds_dwordx4 v130, s[8:9]
	s_add_i32 s8, s66, 0x4000
	s_add_i32 s10, s66, 0xc000
	v_add_u32_e32 v133, 0x10000, v131
	s_mov_b32 m0, s8
	global_load_lds_dwordx4 v133, s[2:3]
	s_add_u32 s8, s6, 0x10000
	s_addc_u32 s9, s7, 0
	s_mov_b32 m0, s10
	global_load_lds_dwordx4 v130, s[8:9]
	s_add_i32 s8, s66, 0x6000
	s_add_i32 s10, s66, 0xe000
	v_and_b32_e32 v3, 15, v2
	v_lshlrev_b32_e32 v5, 2, v2
	v_add_u32_e32 v135, 0x18000, v131
	s_mov_b32 m0, s8
	global_load_lds_dwordx4 v135, s[2:3]
	s_add_u32 s8, s6, 0x18000
	v_and_b32_e32 v4, 48, v2
	v_lshlrev_b32_e32 v3, 6, v3
	v_and_b32_e32 v5, 32, v5
	s_addc_u32 s9, s7, 0
	s_mov_b32 m0, s10
	global_load_lds_dwordx4 v130, s[8:9]
	v_bitop3_b32 v139, v3, v5, v4 bitop3:0x36
	v_lshlrev_b32_e32 v3, 7, v2
	v_lshlrev_b32_e32 v2, 6, v2
	v_and_b32_e32 v143, 0xffffc000, v2
	v_and_b32_e32 v2, 0x3c0, v2
	v_bitop3_b32 v145, v2, v5, v4 bitop3:0x36
	v_mov_b32_e32 v2, 0
	s_mov_b32 s30, 0
	v_and_b32_e32 v141, 0x6000, v3
	v_or_b32_e32 v144, 0x800, v143
	v_or_b32_e32 v146, 0x1000, v143
	v_or_b32_e32 v147, 0x1800, v143
	v_or_b32_e32 v148, 0x2000, v143
	v_or_b32_e32 v149, 0x2800, v143
	v_or_b32_e32 v150, 0x3000, v143
	v_or_b32_e32 v151, 0x3800, v143
	s_mov_b64 s[8:9], 0x80
	v_mov_b32_e32 v3, v2
	v_mov_b32_e32 v4, v2
	v_mov_b32_e32 v5, v2
	v_mov_b32_e32 v6, v2
	v_mov_b32_e32 v7, v2
	v_mov_b32_e32 v8, v2
	v_mov_b32_e32 v9, v2
	v_mov_b32_e32 v10, v2
	v_mov_b32_e32 v11, v2
	v_mov_b32_e32 v12, v2
	v_mov_b32_e32 v13, v2
	v_mov_b32_e32 v14, v2
	v_mov_b32_e32 v15, v2
	v_mov_b32_e32 v16, v2
	v_mov_b32_e32 v17, v2
	v_mov_b32_e32 v18, v2
	v_mov_b32_e32 v19, v2
	v_mov_b32_e32 v20, v2
	v_mov_b32_e32 v21, v2
	v_mov_b32_e32 v22, v2
	v_mov_b32_e32 v23, v2
	v_mov_b32_e32 v24, v2
	v_mov_b32_e32 v25, v2
	v_mov_b32_e32 v26, v2
	v_mov_b32_e32 v27, v2
	v_mov_b32_e32 v28, v2
	v_mov_b32_e32 v29, v2
	v_mov_b32_e32 v30, v2
	v_mov_b32_e32 v31, v2
	v_mov_b32_e32 v32, v2
	v_mov_b32_e32 v33, v2
	v_mov_b32_e32 v34, v2
	v_mov_b32_e32 v35, v2
	v_mov_b32_e32 v36, v2
	v_mov_b32_e32 v37, v2
	v_mov_b32_e32 v38, v2
	v_mov_b32_e32 v39, v2
	v_mov_b32_e32 v40, v2
	v_mov_b32_e32 v41, v2
	v_mov_b32_e32 v42, v2
	v_mov_b32_e32 v43, v2
	v_mov_b32_e32 v44, v2
	v_mov_b32_e32 v45, v2
	v_mov_b32_e32 v46, v2
	v_mov_b32_e32 v47, v2
	v_mov_b32_e32 v48, v2
	v_mov_b32_e32 v49, v2
	v_mov_b32_e32 v50, v2
	v_mov_b32_e32 v51, v2
	v_mov_b32_e32 v52, v2
	v_mov_b32_e32 v53, v2
	v_mov_b32_e32 v54, v2
	v_mov_b32_e32 v55, v2
	v_mov_b32_e32 v56, v2
	v_mov_b32_e32 v57, v2
	v_mov_b32_e32 v58, v2
	v_mov_b32_e32 v59, v2
	v_mov_b32_e32 v60, v2
	v_mov_b32_e32 v61, v2
	v_mov_b32_e32 v62, v2
	v_mov_b32_e32 v63, v2
	v_mov_b32_e32 v64, v2
	v_mov_b32_e32 v65, v2
	v_mov_b32_e32 v66, v2
	v_mov_b32_e32 v67, v2
	v_mov_b32_e32 v68, v2
	v_mov_b32_e32 v69, v2
	v_mov_b32_e32 v70, v2
	v_mov_b32_e32 v71, v2
	v_mov_b32_e32 v72, v2
	v_mov_b32_e32 v73, v2
	v_mov_b32_e32 v74, v2
	v_mov_b32_e32 v75, v2
	v_mov_b32_e32 v76, v2
	v_mov_b32_e32 v77, v2
	v_mov_b32_e32 v78, v2
	v_mov_b32_e32 v79, v2
	v_mov_b32_e32 v80, v2
	v_mov_b32_e32 v81, v2
	v_mov_b32_e32 v82, v2
	v_mov_b32_e32 v83, v2
	v_mov_b32_e32 v84, v2
	v_mov_b32_e32 v85, v2
	v_mov_b32_e32 v86, v2
	v_mov_b32_e32 v87, v2
	v_mov_b32_e32 v88, v2
	v_mov_b32_e32 v89, v2
	v_mov_b32_e32 v90, v2
	v_mov_b32_e32 v91, v2
	v_mov_b32_e32 v92, v2
	v_mov_b32_e32 v93, v2
	v_mov_b32_e32 v94, v2
	v_mov_b32_e32 v95, v2
	v_mov_b32_e32 v96, v2
	v_mov_b32_e32 v97, v2
	v_mov_b32_e32 v98, v2
	v_mov_b32_e32 v99, v2
	v_mov_b32_e32 v100, v2
	v_mov_b32_e32 v101, v2
	v_mov_b32_e32 v102, v2
	v_mov_b32_e32 v103, v2
	v_mov_b32_e32 v104, v2
	v_mov_b32_e32 v105, v2
	v_mov_b32_e32 v106, v2
	v_mov_b32_e32 v107, v2
	v_mov_b32_e32 v108, v2
	v_mov_b32_e32 v109, v2
	v_mov_b32_e32 v110, v2
	v_mov_b32_e32 v111, v2
	v_mov_b32_e32 v112, v2
	v_mov_b32_e32 v113, v2
	v_mov_b32_e32 v114, v2
	v_mov_b32_e32 v115, v2
	v_mov_b32_e32 v116, v2
	v_mov_b32_e32 v117, v2
	v_mov_b32_e32 v118, v2
	v_mov_b32_e32 v119, v2
	v_mov_b32_e32 v120, v2
	v_mov_b32_e32 v121, v2
	v_mov_b32_e32 v122, v2
	v_mov_b32_e32 v123, v2
	v_mov_b32_e32 v124, v2
	v_mov_b32_e32 v125, v2
	v_mov_b32_e32 v126, v2
	v_mov_b32_e32 v127, v2
	v_mov_b32_e32 v128, v2
	v_mov_b32_e32 v129, v2
	s_waitcnt vmcnt(0)
	s_barrier
	s_branch .LBB0_107

.LBB0_119:
	s_or_b64 exec, exec, s[6:7]
	s_mul_i32 s6, s4, 0x30000
	s_mul_hi_i32 s5, s4, 0x30000
	s_add_u32 s6, s21, s6
	v_mov_b32_e32 v4, v176
	s_waitcnt vmcnt(0)
	s_barrier
	s_addc_u32 s7, s25, s5
	s_nop 0
	v_lshlrev_b32_e32 v5, 4, v4
	v_and_b32_e32 v6, 32, v4
	v_readfirstlane_b32 s5, v4
	v_bfe_i32 v7, v4, 3, 25
	v_lshrrev_b32_e32 v8, 2, v4
	v_bitop3_b32 v5, v5, v6, 48 bitop3:0x6c
	s_lshl_b32 s5, s5, 4
	v_bfi_b32 v7, -16, v7, v8
	v_lshrrev_b32_e32 v8, 1, v4
	v_lshrrev_b32_e32 v5, 1, v5
	s_and_b32 s8, s5, 0xfffffc00
	v_and_or_b32 v5, v8, 32, v5
	v_mul_lo_u32 v6, v7, s38
	s_cmp_lg_u32 0, -1
	v_lshlrev_b32_e32 v16, 1, v5
	v_or_b32_e32 v5, v6, v5
	s_cselect_b32 s9, 0, 0
	v_add_lshl_u32 v135, v7, s15, 9
	v_lshlrev_b32_e32 v17, 1, v5
	s_add_i32 s8, s8, s9
	s_barrier
	v_or_b32_e32 v5, v135, v16
	s_mov_b32 m0, s8
	global_load_lds_dwordx4 v5, s[2:3]
	s_add_i32 s9, s8, 0x8000
	s_mov_b32 m0, s9
	global_load_lds_dwordx4 v17, s[6:7]
	s_add_i32 s10, s8, 0x2000
	s_add_i32 s29, s8, 0xa000
	v_add_u32_e32 v6, 0x8000, v5
	s_mov_b32 m0, s10
	global_load_lds_dwordx4 v6, s[2:3]
	s_add_u32 s10, s6, 0xc000
	s_addc_u32 s11, s7, 0
	s_mov_b32 m0, s29
	global_load_lds_dwordx4 v17, s[10:11]
	s_add_i32 s10, s8, 0x4000
	s_add_i32 s29, s8, 0xc000
	v_add_u32_e32 v6, 0x10000, v5
	s_mov_b32 m0, s10
	global_load_lds_dwordx4 v6, s[2:3]
	s_add_u32 s10, s6, 0x18000
	s_addc_u32 s11, s7, 0
	s_mov_b32 m0, s29
	global_load_lds_dwordx4 v17, s[10:11]
	s_add_i32 s10, s8, 0x6000
	s_add_i32 s29, s8, 0xe000
	v_add_u32_e32 v5, 0x18000, v5
	s_mov_b32 m0, s10
	global_load_lds_dwordx4 v5, s[2:3]
	s_add_u32 s10, s6, 0x24000
	s_addc_u32 s11, s7, 0
	v_and_b32_e32 v5, 15, v4
	v_lshlrev_b32_e32 v7, 2, v4
	s_mov_b32 m0, s29
	global_load_lds_dwordx4 v17, s[10:11]
	v_and_b32_e32 v6, 48, v4
	v_lshlrev_b32_e32 v5, 6, v5
	v_and_b32_e32 v7, 32, v7
	s_add_u32 s10, s6, 0x80
	v_bitop3_b32 v139, v5, v7, v6 bitop3:0x36
	v_lshlrev_b32_e32 v5, 7, v4
	v_lshlrev_b32_e32 v4, 6, v4
	s_addc_u32 s11, s7, 0
	v_and_b32_e32 v146, 0xffffc000, v4
	v_and_b32_e32 v4, 0x3c0, v4
	v_lshl_add_u64 v[14:15], s[62:63], 0, v[2:3]
	s_add_u32 s30, s2, 0x80
	v_mov_b32_e32 v2, 0
	s_mov_b32 s5, 0
	v_add_u32_e32 v141, 0x8000, v135
	v_add_u32_e32 v143, 0x10000, v135
	v_add_u32_e32 v144, 0x18000, v135
	v_and_b32_e32 v145, 0x6000, v5
	v_or_b32_e32 v147, 0x800, v146
	v_bitop3_b32 v148, v4, v7, v6 bitop3:0x36
	v_or_b32_e32 v149, 0x1000, v146
	v_or_b32_e32 v150, 0x1800, v146
	v_or_b32_e32 v151, 0x2000, v146
	v_or_b32_e32 v162, 0x2800, v146
	v_or_b32_e32 v163, 0x3000, v146
	v_or_b32_e32 v164, 0x3800, v146
	s_addc_u32 s66, s3, 0
	s_mov_b64 s[6:7], 0
	s_mov_b32 s67, 0
	v_mov_b32_e32 v3, v2
	v_mov_b32_e32 v4, v2
	v_mov_b32_e32 v5, v2
	v_mov_b32_e32 v6, v2
	v_mov_b32_e32 v7, v2
	v_mov_b32_e32 v8, v2
	v_mov_b32_e32 v9, v2
	v_mov_b32_e32 v10, v2
	v_mov_b32_e32 v11, v2
	v_mov_b32_e32 v12, v2
	v_mov_b32_e32 v13, v2
	v_mov_b32_e32 v18, v2
	v_mov_b32_e32 v19, v2
	v_mov_b32_e32 v20, v2
	v_mov_b32_e32 v21, v2
	v_mov_b32_e32 v22, v2
	v_mov_b32_e32 v23, v2
	v_mov_b32_e32 v24, v2
	v_mov_b32_e32 v25, v2
	v_mov_b32_e32 v26, v2
	v_mov_b32_e32 v27, v2
	v_mov_b32_e32 v28, v2
	v_mov_b32_e32 v29, v2
	v_mov_b32_e32 v30, v2
	v_mov_b32_e32 v31, v2
	v_mov_b32_e32 v32, v2
	v_mov_b32_e32 v33, v2
	v_mov_b32_e32 v34, v2
	v_mov_b32_e32 v35, v2
	v_mov_b32_e32 v36, v2
	v_mov_b32_e32 v37, v2
	v_mov_b32_e32 v38, v2
	v_mov_b32_e32 v39, v2
	v_mov_b32_e32 v40, v2
	v_mov_b32_e32 v41, v2
	v_mov_b32_e32 v42, v2
	v_mov_b32_e32 v43, v2
	v_mov_b32_e32 v44, v2
	v_mov_b32_e32 v45, v2
	v_mov_b32_e32 v46, v2
	v_mov_b32_e32 v47, v2
	v_mov_b32_e32 v48, v2
	v_mov_b32_e32 v49, v2
	v_mov_b32_e32 v50, v2
	v_mov_b32_e32 v51, v2
	v_mov_b32_e32 v52, v2
	v_mov_b32_e32 v53, v2
	v_mov_b32_e32 v54, v2
	v_mov_b32_e32 v55, v2
	v_mov_b32_e32 v56, v2
	v_mov_b32_e32 v57, v2
	v_mov_b32_e32 v58, v2
	v_mov_b32_e32 v59, v2
	v_mov_b32_e32 v60, v2
	v_mov_b32_e32 v61, v2
	v_mov_b32_e32 v62, v2
	v_mov_b32_e32 v63, v2
	v_mov_b32_e32 v64, v2
	v_mov_b32_e32 v65, v2
	v_mov_b32_e32 v66, v2
	v_mov_b32_e32 v67, v2
	v_mov_b32_e32 v68, v2
	v_mov_b32_e32 v69, v2
	v_mov_b32_e32 v70, v2
	v_mov_b32_e32 v71, v2
	v_mov_b32_e32 v72, v2
	v_mov_b32_e32 v73, v2
	v_mov_b32_e32 v74, v2
	v_mov_b32_e32 v75, v2
	v_mov_b32_e32 v76, v2
	v_mov_b32_e32 v77, v2
	v_mov_b32_e32 v78, v2
	v_mov_b32_e32 v79, v2
	v_mov_b32_e32 v80, v2
	v_mov_b32_e32 v81, v2
	v_mov_b32_e32 v82, v2
	v_mov_b32_e32 v83, v2
	v_mov_b32_e32 v84, v2
	v_mov_b32_e32 v85, v2
	v_mov_b32_e32 v86, v2
	v_mov_b32_e32 v87, v2
	v_mov_b32_e32 v88, v2
	v_mov_b32_e32 v89, v2
	v_mov_b32_e32 v90, v2
	v_mov_b32_e32 v91, v2
	v_mov_b32_e32 v92, v2
	v_mov_b32_e32 v93, v2
	v_mov_b32_e32 v94, v2
	v_mov_b32_e32 v95, v2
	v_mov_b32_e32 v96, v2
	v_mov_b32_e32 v97, v2
	v_mov_b32_e32 v98, v2
	v_mov_b32_e32 v99, v2
	v_mov_b32_e32 v100, v2
	v_mov_b32_e32 v101, v2
	v_mov_b32_e32 v102, v2
	v_mov_b32_e32 v103, v2
	v_mov_b32_e32 v104, v2
	v_mov_b32_e32 v105, v2
	v_mov_b32_e32 v106, v2
	v_mov_b32_e32 v107, v2
	v_mov_b32_e32 v108, v2
	v_mov_b32_e32 v109, v2
	v_mov_b32_e32 v110, v2
	v_mov_b32_e32 v111, v2
	v_mov_b32_e32 v112, v2
	v_mov_b32_e32 v113, v2
	v_mov_b32_e32 v114, v2
	v_mov_b32_e32 v115, v2
	v_mov_b32_e32 v116, v2
	v_mov_b32_e32 v117, v2
	v_mov_b32_e32 v118, v2
	v_mov_b32_e32 v119, v2
	v_mov_b32_e32 v120, v2
	v_mov_b32_e32 v121, v2
	v_mov_b32_e32 v122, v2
	v_mov_b32_e32 v123, v2
	v_mov_b32_e32 v124, v2
	v_mov_b32_e32 v125, v2
	v_mov_b32_e32 v126, v2
	v_mov_b32_e32 v127, v2
	v_mov_b32_e32 v128, v2
	v_mov_b32_e32 v129, v2
	v_mov_b32_e32 v130, v2
	v_mov_b32_e32 v131, v2
	v_mov_b32_e32 v132, v2
	v_mov_b32_e32 v133, v2
	s_waitcnt vmcnt(0)
	s_barrier
	s_branch .LBB0_121

.LBB0_201:
	s_lshl_b32 s2, s16, 6
	s_and_b32 s2, s2, 0x1c0
	s_ashr_i32 s3, s16, 3
	s_add_i32 s2, s2, s3
	s_ashr_i32 s6, s2, 31
	s_lshr_b32 s6, s6, 27
	s_add_i32 s6, s2, s6
	s_ashr_i32 s6, s6, 5
	s_lshl_b32 s3, s3, 8
	s_lshl_b32 s7, s6, 11
	s_and_b32 s3, s3, 0x700
	s_or_b32 s15, s7, s3
	s_lshl_b32 s3, s6, 10
	s_lshl_b32 s2, s2, 5
	s_sub_i32 s2, s2, s3
	v_mov_b32_e32 v2, v176
	s_and_b32 s8, s2, 0xffffff00
	s_nop 0
	v_readfirstlane_b32 s2, v2
	v_lshlrev_b32_e32 v3, 4, v2
	v_and_b32_e32 v4, 32, v2
	v_bfe_i32 v5, v2, 3, 25
	v_lshrrev_b32_e32 v6, 2, v2
	s_lshl_b32 s2, s2, 4
	v_bfi_b32 v5, -16, v5, v6
	v_bitop3_b32 v3, v3, v4, 48 bitop3:0x6c
	s_and_b32 s17, s2, 0xfffffc00
	v_and_or_b32 v3, v2, 64, v3
	v_add_u32_e32 v4, s8, v5
	s_cmp_lg_u32 0, -1
	v_lshl_or_b32 v126, v4, 11, v3
	v_add_u32_e32 v4, s15, v5
	s_cselect_b32 s2, 0, 0
	s_add_i32 s17, s17, s2
	s_barrier
	v_lshl_or_b32 v127, v4, 11, v3
	s_mov_b32 m0, s17
	global_load_lds_dwordx4 v127, s[40:41]
	s_add_i32 s18, s17, 0x8000
	s_mov_b32 m0, s18
	global_load_lds_dwordx4 v126, s[44:45]
	s_add_i32 s2, s17, 0x2000
	s_add_i32 s6, s17, 0xa000
	v_add_u32_e32 v128, 0x20000, v127
	s_mov_b32 m0, s2
	global_load_lds_dwordx4 v128, s[40:41]
	s_add_u32 s2, s44, 0x20000
	s_addc_u32 s3, s45, 0
	s_mov_b32 m0, s6
	global_load_lds_dwordx4 v126, s[2:3]
	s_add_i32 s2, s17, 0x4000
	s_add_i32 s6, s17, 0xc000
	v_add_u32_e32 v129, 0x40000, v127
	s_mov_b32 m0, s2
	global_load_lds_dwordx4 v129, s[40:41]
	s_add_u32 s2, s44, 0x40000
	s_addc_u32 s3, s45, 0
	s_mov_b32 m0, s6
	global_load_lds_dwordx4 v126, s[2:3]
	s_add_i32 s2, s17, 0x6000
	s_add_i32 s6, s17, 0xe000
	v_and_b32_e32 v3, 15, v2
	v_lshlrev_b32_e32 v5, 2, v2
	v_add_u32_e32 v130, 0x60000, v127
	s_mov_b32 m0, s2
	global_load_lds_dwordx4 v130, s[40:41]
	s_add_u32 s2, s44, 0x60000
	v_and_b32_e32 v4, 48, v2
	v_lshlrev_b32_e32 v3, 6, v3
	v_and_b32_e32 v5, 32, v5
	s_addc_u32 s3, s45, 0
	s_mov_b32 m0, s6
	global_load_lds_dwordx4 v126, s[2:3]
	v_bitop3_b32 v131, v3, v5, v4 bitop3:0x36
	v_lshlrev_b32_e32 v3, 7, v2
	v_lshlrev_b32_e32 v2, 6, v2
	v_and_b32_e32 v133, 0xffffc000, v2
	v_and_b32_e32 v2, 0x3c0, v2
	v_bitop3_b32 v135, v2, v5, v4 bitop3:0x36
	v_mov_b32_e32 v2, 0
	s_mov_b32 s9, 0
	v_and_b32_e32 v132, 0x6000, v3
	v_or_b32_e32 v134, 0x800, v133
	v_or_b32_e32 v136, 0x1000, v133
	v_or_b32_e32 v137, 0x1800, v133
	v_or_b32_e32 v138, 0x2000, v133
	v_or_b32_e32 v139, 0x2800, v133
	v_or_b32_e32 v140, 0x3000, v133
	v_or_b32_e32 v141, 0x3800, v133
	s_mov_b64 s[2:3], s[48:49]
	s_mov_b64 s[6:7], s[46:47]
	v_mov_b32_e32 v3, v2
	v_mov_b32_e32 v4, v2
	v_mov_b32_e32 v5, v2
	v_mov_b32_e32 v6, v2
	v_mov_b32_e32 v7, v2
	v_mov_b32_e32 v8, v2
	v_mov_b32_e32 v9, v2
	v_mov_b32_e32 v10, v2
	v_mov_b32_e32 v11, v2
	v_mov_b32_e32 v12, v2
	v_mov_b32_e32 v13, v2
	v_mov_b32_e32 v14, v2
	v_mov_b32_e32 v15, v2
	v_mov_b32_e32 v16, v2
	v_mov_b32_e32 v17, v2
	v_mov_b32_e32 v18, v2
	v_mov_b32_e32 v19, v2
	v_mov_b32_e32 v20, v2
	v_mov_b32_e32 v21, v2
	v_mov_b32_e32 v22, v2
	v_mov_b32_e32 v23, v2
	v_mov_b32_e32 v24, v2
	v_mov_b32_e32 v25, v2
	v_mov_b32_e32 v26, v2
	v_mov_b32_e32 v27, v2
	v_mov_b32_e32 v28, v2
	v_mov_b32_e32 v29, v2
	v_mov_b32_e32 v30, v2
	v_mov_b32_e32 v31, v2
	v_mov_b32_e32 v32, v2
	v_mov_b32_e32 v33, v2
	v_mov_b32_e32 v34, v2
	v_mov_b32_e32 v35, v2
	v_mov_b32_e32 v36, v2
	v_mov_b32_e32 v37, v2
	v_mov_b32_e32 v38, v2
	v_mov_b32_e32 v39, v2
	v_mov_b32_e32 v40, v2
	v_mov_b32_e32 v41, v2
	v_mov_b32_e32 v42, v2
	v_mov_b32_e32 v43, v2
	v_mov_b32_e32 v44, v2
	v_mov_b32_e32 v45, v2
	v_mov_b32_e32 v46, v2
	v_mov_b32_e32 v47, v2
	v_mov_b32_e32 v48, v2
	v_mov_b32_e32 v49, v2
	v_mov_b32_e32 v50, v2
	v_mov_b32_e32 v51, v2
	v_mov_b32_e32 v52, v2
	v_mov_b32_e32 v53, v2
	v_mov_b32_e32 v54, v2
	v_mov_b32_e32 v55, v2
	v_mov_b32_e32 v56, v2
	v_mov_b32_e32 v57, v2
	v_mov_b32_e32 v58, v2
	v_mov_b32_e32 v59, v2
	v_mov_b32_e32 v60, v2
	v_mov_b32_e32 v61, v2
	v_mov_b32_e32 v62, v2
	v_mov_b32_e32 v63, v2
	v_mov_b32_e32 v64, v2
	v_mov_b32_e32 v65, v2
	v_mov_b32_e32 v66, v2
	v_mov_b32_e32 v67, v2
	v_mov_b32_e32 v68, v2
	v_mov_b32_e32 v69, v2
	v_mov_b32_e32 v70, v2
	v_mov_b32_e32 v71, v2
	v_mov_b32_e32 v72, v2
	v_mov_b32_e32 v73, v2
	v_mov_b32_e32 v74, v2
	v_mov_b32_e32 v75, v2
	v_mov_b32_e32 v76, v2
	v_mov_b32_e32 v77, v2
	v_mov_b32_e32 v78, v2
	v_mov_b32_e32 v79, v2
	v_mov_b32_e32 v80, v2
	v_mov_b32_e32 v81, v2
	v_mov_b32_e32 v82, v2
	v_mov_b32_e32 v83, v2
	v_mov_b32_e32 v84, v2
	v_mov_b32_e32 v85, v2
	v_mov_b32_e32 v86, v2
	v_mov_b32_e32 v87, v2
	v_mov_b32_e32 v88, v2
	v_mov_b32_e32 v89, v2
	v_mov_b32_e32 v90, v2
	v_mov_b32_e32 v91, v2
	v_mov_b32_e32 v92, v2
	v_mov_b32_e32 v93, v2
	v_mov_b32_e32 v94, v2
	v_mov_b32_e32 v95, v2
	v_mov_b32_e32 v96, v2
	v_mov_b32_e32 v97, v2
	v_mov_b32_e32 v98, v2
	v_mov_b32_e32 v99, v2
	v_mov_b32_e32 v100, v2
	v_mov_b32_e32 v101, v2
	v_mov_b32_e32 v102, v2
	v_mov_b32_e32 v103, v2
	v_mov_b32_e32 v104, v2
	v_mov_b32_e32 v105, v2
	v_mov_b32_e32 v106, v2
	v_mov_b32_e32 v107, v2
	v_mov_b32_e32 v108, v2
	v_mov_b32_e32 v109, v2
	v_mov_b32_e32 v110, v2
	v_mov_b32_e32 v111, v2
	v_mov_b32_e32 v112, v2
	v_mov_b32_e32 v113, v2
	v_mov_b32_e32 v114, v2
	v_mov_b32_e32 v115, v2
	v_mov_b32_e32 v116, v2
	v_mov_b32_e32 v117, v2
	v_mov_b32_e32 v118, v2
	v_mov_b32_e32 v119, v2
	v_mov_b32_e32 v120, v2
	v_mov_b32_e32 v121, v2
	v_mov_b32_e32 v122, v2
	v_mov_b32_e32 v123, v2
	v_mov_b32_e32 v124, v2
	v_mov_b32_e32 v125, v2
	v_mov_b32_e32 v142, v2
	v_mov_b32_e32 v143, v2
	v_mov_b32_e32 v144, v2
	v_mov_b32_e32 v145, v2
	s_waitcnt vmcnt(0)
	s_barrier
	s_branch .LBB0_203

.LBB0_212:
	s_lshl_b32 s10, s19, 6
	s_and_b32 s10, s10, 0x1c0
	s_ashr_i32 s11, s19, 3
	s_add_i32 s10, s10, s11
	s_ashr_i32 s12, s10, 31
	s_lshr_b32 s12, s12, 27
	s_add_i32 s12, s10, s12
	s_ashr_i32 s12, s12, 5
	s_lshl_b32 s11, s11, 8
	s_lshl_b32 s13, s12, 11
	s_and_b32 s11, s11, 0x700
	s_or_b32 s21, s13, s11
	s_lshl_b32 s11, s12, 10
	s_lshl_b32 s10, s10, 5
	s_sub_i32 s10, s10, s11
	v_mov_b32_e32 v2, v176
	s_and_b32 s25, s10, 0xffffff00
	s_nop 0
	v_readfirstlane_b32 s10, v2
	s_lshl_b32 s10, s10, 4
	v_lshlrev_b32_e32 v0, 4, v2
	v_and_b32_e32 v3, 32, v2
	v_bfe_i32 v4, v2, 3, 25
	v_lshrrev_b32_e32 v5, 2, v2
	s_and_b32 s40, s10, 0xfffffc00
	v_bfi_b32 v4, -16, v4, v5
	v_bitop3_b32 v0, v0, v3, 48 bitop3:0x6c
	s_cmp_lg_u32 0, -1
	v_and_or_b32 v3, v2, 64, v0
	v_add_u32_e32 v0, s25, v4
	v_add_u32_e32 v4, s21, v4
	s_cselect_b32 s10, 0, 0
	s_add_i32 s40, s40, s10
	s_barrier
	v_lshl_or_b32 v130, v4, 11, v3
	s_mov_b32 m0, s40
	global_load_lds_dwordx4 v130, s[60:61]
	v_lshl_or_b32 v0, v0, 11, v3
	s_add_i32 s41, s40, 0x8000
	s_mov_b32 m0, s41
	global_load_lds_dwordx4 v0, s[46:47]
	s_add_i32 s10, s40, 0x2000
	s_add_i32 s12, s40, 0xa000
	v_add_u32_e32 v131, 0x20000, v130
	s_mov_b32 m0, s10
	global_load_lds_dwordx4 v131, s[60:61]
	s_add_u32 s10, s46, 0x20000
	s_addc_u32 s11, s47, 0
	s_mov_b32 m0, s12
	global_load_lds_dwordx4 v0, s[10:11]
	s_add_i32 s10, s40, 0x4000
	s_add_i32 s12, s40, 0xc000
	v_add_u32_e32 v132, 0x40000, v130
	s_mov_b32 m0, s10
	global_load_lds_dwordx4 v132, s[60:61]
	s_add_u32 s10, s46, 0x40000
	s_addc_u32 s11, s47, 0
	s_mov_b32 m0, s12
	global_load_lds_dwordx4 v0, s[10:11]
	s_add_i32 s10, s40, 0x6000
	s_add_i32 s12, s40, 0xe000
	v_and_b32_e32 v3, 15, v2
	v_lshlrev_b32_e32 v5, 2, v2
	v_add_u32_e32 v133, 0x60000, v130
	s_mov_b32 m0, s10
	global_load_lds_dwordx4 v133, s[60:61]
	s_add_u32 s10, s46, 0x60000
	v_and_b32_e32 v4, 48, v2
	v_lshlrev_b32_e32 v3, 6, v3
	v_and_b32_e32 v5, 32, v5
	s_addc_u32 s11, s47, 0
	s_mov_b32 m0, s12
	global_load_lds_dwordx4 v0, s[10:11]
	v_bitop3_b32 v134, v3, v5, v4 bitop3:0x36
	v_lshlrev_b32_e32 v3, 7, v2
	v_lshlrev_b32_e32 v2, 6, v2
	v_and_b32_e32 v140, 0xffffc000, v2
	v_and_b32_e32 v2, 0x3c0, v2
	v_bitop3_b32 v142, v2, v5, v4 bitop3:0x36
	v_mov_b32_e32 v2, 0
	s_mov_b32 s30, 0
	v_and_b32_e32 v135, 0x6000, v3
	v_or_b32_e32 v141, 0x800, v140
	v_or_b32_e32 v143, 0x1000, v140
	v_or_b32_e32 v144, 0x1800, v140
	v_or_b32_e32 v145, 0x2000, v140
	v_or_b32_e32 v146, 0x2800, v140
	v_or_b32_e32 v147, 0x3000, v140
	v_or_b32_e32 v148, 0x3800, v140
	s_mov_b64 s[10:11], s[8:9]
	s_mov_b64 s[12:13], s[6:7]
	v_mov_b32_e32 v3, v2
	v_mov_b32_e32 v4, v2
	v_mov_b32_e32 v5, v2
	v_mov_b32_e32 v6, v2
	v_mov_b32_e32 v7, v2
	v_mov_b32_e32 v8, v2
	v_mov_b32_e32 v9, v2
	v_mov_b32_e32 v10, v2
	v_mov_b32_e32 v11, v2
	v_mov_b32_e32 v12, v2
	v_mov_b32_e32 v13, v2
	v_mov_b32_e32 v14, v2
	v_mov_b32_e32 v15, v2
	v_mov_b32_e32 v16, v2
	v_mov_b32_e32 v17, v2
	v_mov_b32_e32 v18, v2
	v_mov_b32_e32 v19, v2
	v_mov_b32_e32 v20, v2
	v_mov_b32_e32 v21, v2
	v_mov_b32_e32 v22, v2
	v_mov_b32_e32 v23, v2
	v_mov_b32_e32 v24, v2
	v_mov_b32_e32 v25, v2
	v_mov_b32_e32 v26, v2
	v_mov_b32_e32 v27, v2
	v_mov_b32_e32 v28, v2
	v_mov_b32_e32 v29, v2
	v_mov_b32_e32 v30, v2
	v_mov_b32_e32 v31, v2
	v_mov_b32_e32 v32, v2
	v_mov_b32_e32 v33, v2
	v_mov_b32_e32 v34, v2
	v_mov_b32_e32 v35, v2
	v_mov_b32_e32 v36, v2
	v_mov_b32_e32 v37, v2
	v_mov_b32_e32 v38, v2
	v_mov_b32_e32 v39, v2
	v_mov_b32_e32 v40, v2
	v_mov_b32_e32 v41, v2
	v_mov_b32_e32 v42, v2
	v_mov_b32_e32 v43, v2
	v_mov_b32_e32 v44, v2
	v_mov_b32_e32 v45, v2
	v_mov_b32_e32 v46, v2
	v_mov_b32_e32 v47, v2
	v_mov_b32_e32 v48, v2
	v_mov_b32_e32 v49, v2
	v_mov_b32_e32 v50, v2
	v_mov_b32_e32 v51, v2
	v_mov_b32_e32 v52, v2
	v_mov_b32_e32 v53, v2
	v_mov_b32_e32 v54, v2
	v_mov_b32_e32 v55, v2
	v_mov_b32_e32 v56, v2
	v_mov_b32_e32 v57, v2
	v_mov_b32_e32 v58, v2
	v_mov_b32_e32 v59, v2
	v_mov_b32_e32 v60, v2
	v_mov_b32_e32 v61, v2
	v_mov_b32_e32 v62, v2
	v_mov_b32_e32 v63, v2
	v_mov_b32_e32 v64, v2
	v_mov_b32_e32 v65, v2
	v_mov_b32_e32 v66, v2
	v_mov_b32_e32 v67, v2
	v_mov_b32_e32 v68, v2
	v_mov_b32_e32 v69, v2
	v_mov_b32_e32 v70, v2
	v_mov_b32_e32 v71, v2
	v_mov_b32_e32 v72, v2
	v_mov_b32_e32 v73, v2
	v_mov_b32_e32 v74, v2
	v_mov_b32_e32 v75, v2
	v_mov_b32_e32 v76, v2
	v_mov_b32_e32 v77, v2
	v_mov_b32_e32 v78, v2
	v_mov_b32_e32 v79, v2
	v_mov_b32_e32 v80, v2
	v_mov_b32_e32 v81, v2
	v_mov_b32_e32 v82, v2
	v_mov_b32_e32 v83, v2
	v_mov_b32_e32 v84, v2
	v_mov_b32_e32 v85, v2
	v_mov_b32_e32 v86, v2
	v_mov_b32_e32 v87, v2
	v_mov_b32_e32 v88, v2
	v_mov_b32_e32 v89, v2
	v_mov_b32_e32 v90, v2
	v_mov_b32_e32 v91, v2
	v_mov_b32_e32 v92, v2
	v_mov_b32_e32 v93, v2
	v_mov_b32_e32 v94, v2
	v_mov_b32_e32 v95, v2
	v_mov_b32_e32 v96, v2
	v_mov_b32_e32 v97, v2
	v_mov_b32_e32 v98, v2
	v_mov_b32_e32 v99, v2
	v_mov_b32_e32 v100, v2
	v_mov_b32_e32 v101, v2
	v_mov_b32_e32 v102, v2
	v_mov_b32_e32 v103, v2
	v_mov_b32_e32 v104, v2
	v_mov_b32_e32 v105, v2
	v_mov_b32_e32 v106, v2
	v_mov_b32_e32 v107, v2
	v_mov_b32_e32 v108, v2
	v_mov_b32_e32 v109, v2
	v_mov_b32_e32 v110, v2
	v_mov_b32_e32 v111, v2
	v_mov_b32_e32 v112, v2
	v_mov_b32_e32 v113, v2
	v_mov_b32_e32 v114, v2
	v_mov_b32_e32 v115, v2
	v_mov_b32_e32 v116, v2
	v_mov_b32_e32 v117, v2
	v_mov_b32_e32 v118, v2
	v_mov_b32_e32 v119, v2
	v_mov_b32_e32 v120, v2
	v_mov_b32_e32 v121, v2
	v_mov_b32_e32 v122, v2
	v_mov_b32_e32 v123, v2
	v_mov_b32_e32 v124, v2
	v_mov_b32_e32 v125, v2
	v_mov_b32_e32 v126, v2
	v_mov_b32_e32 v127, v2
	v_mov_b32_e32 v128, v2
	v_mov_b32_e32 v129, v2
	s_waitcnt vmcnt(0)
	s_barrier
	s_branch .LBB0_214

.LBB0_223:
	s_lshl_b32 s2, s18, 4
	s_and_b32 s2, s2, 0x70
	s_mul_i32 s2, s2, s10
	s_ashr_i32 s3, s18, 3
	s_add_i32 s2, s2, s3
	s_abs_i32 s7, s2
	s_mul_hi_u32 s8, s7, s17
	s_mul_i32 s9, s8, s16
	s_sub_i32 s7, s7, s9
	s_ashr_i32 s6, s2, 31
	s_add_i32 s9, s8, 1
	s_sub_i32 s15, s7, s16
	s_cmp_ge_u32 s7, s16
	s_cselect_b32 s8, s9, s8
	s_cselect_b32 s7, s15, s7
	s_add_i32 s9, s8, 1
	s_cmp_ge_u32 s7, s16
	s_cselect_b32 s7, s9, s8
	s_xor_b32 s7, s7, s6
	s_sub_i32 s6, s7, s6
	s_mul_i32 s7, s6, s16
	s_sub_i32 s2, s2, s7
	s_lshl_b32 s2, s2, 5
	v_mov_b32_e32 v2, v176
	s_lshl_b32 s3, s3, 8
	s_and_b32 s15, s2, 0xffffff00
	s_lshl_b32 s6, s6, 11
	v_readfirstlane_b32 s2, v2
	s_and_b32 s3, s3, 0x700
	s_lshl_b32 s2, s2, 4
	s_or_b32 s19, s3, s6
	v_lshlrev_b32_e32 v0, 4, v2
	v_and_b32_e32 v3, 32, v2
	v_bfe_i32 v4, v2, 3, 25
	v_lshrrev_b32_e32 v5, 2, v2
	s_and_b32 s25, s2, 0xfffffc00
	v_bfi_b32 v4, -16, v4, v5
	v_bitop3_b32 v0, v0, v3, 48 bitop3:0x6c
	s_cmp_lg_u32 0, -1
	v_and_or_b32 v3, v2, 64, v0
	v_add_u32_e32 v0, s15, v4
	v_add_u32_e32 v4, s19, v4
	s_cselect_b32 s2, 0, 0
	s_add_i32 s25, s25, s2
	s_barrier
	v_lshl_or_b32 v130, v4, 11, v3
	s_mov_b32 m0, s25
	global_load_lds_dwordx4 v130, s[60:61]
	v_lshl_or_b32 v0, v0, 11, v3
	s_add_i32 s30, s25, 0x8000
	s_mov_b32 m0, s30
	global_load_lds_dwordx4 v0, s[46:47]
	s_add_i32 s2, s25, 0x2000
	s_add_i32 s6, s25, 0xa000
	v_add_u32_e32 v131, 0x20000, v130
	s_mov_b32 m0, s2
	global_load_lds_dwordx4 v131, s[60:61]
	s_add_u32 s2, s46, 0x20000
	s_addc_u32 s3, s47, 0
	s_mov_b32 m0, s6
	global_load_lds_dwordx4 v0, s[2:3]
	s_add_i32 s2, s25, 0x4000
	s_add_i32 s6, s25, 0xc000
	v_add_u32_e32 v132, 0x40000, v130
	s_mov_b32 m0, s2
	global_load_lds_dwordx4 v132, s[60:61]
	s_add_u32 s2, s46, 0x40000
	s_addc_u32 s3, s47, 0
	s_mov_b32 m0, s6
	global_load_lds_dwordx4 v0, s[2:3]
	s_add_i32 s2, s25, 0x6000
	s_add_i32 s6, s25, 0xe000
	v_and_b32_e32 v3, 15, v2
	v_lshlrev_b32_e32 v5, 2, v2
	v_add_u32_e32 v133, 0x60000, v130
	s_mov_b32 m0, s2
	global_load_lds_dwordx4 v133, s[60:61]
	s_add_u32 s2, s46, 0x60000
	v_and_b32_e32 v4, 48, v2
	v_lshlrev_b32_e32 v3, 6, v3
	v_and_b32_e32 v5, 32, v5
	s_addc_u32 s3, s47, 0
	s_mov_b32 m0, s6
	global_load_lds_dwordx4 v0, s[2:3]
	v_bitop3_b32 v134, v3, v5, v4 bitop3:0x36
	v_lshlrev_b32_e32 v3, 7, v2
	v_lshlrev_b32_e32 v2, 6, v2
	v_and_b32_e32 v136, 0xffffc000, v2
	v_and_b32_e32 v2, 0x3c0, v2
	v_bitop3_b32 v138, v2, v5, v4 bitop3:0x36
	v_mov_b32_e32 v2, 0
	s_mov_b32 s21, 0
	v_and_b32_e32 v135, 0x6000, v3
	v_or_b32_e32 v137, 0x800, v136
	v_or_b32_e32 v139, 0x1000, v136
	v_or_b32_e32 v140, 0x1800, v136
	v_or_b32_e32 v141, 0x2000, v136
	v_or_b32_e32 v142, 0x2800, v136
	v_or_b32_e32 v143, 0x3000, v136
	v_or_b32_e32 v144, 0x3800, v136
	s_mov_b64 s[2:3], s[90:91]
	s_mov_b64 s[6:7], s[78:79]
	v_mov_b32_e32 v3, v2
	v_mov_b32_e32 v4, v2
	v_mov_b32_e32 v5, v2
	v_mov_b32_e32 v6, v2
	v_mov_b32_e32 v7, v2
	v_mov_b32_e32 v8, v2
	v_mov_b32_e32 v9, v2
	v_mov_b32_e32 v10, v2
	v_mov_b32_e32 v11, v2
	v_mov_b32_e32 v12, v2
	v_mov_b32_e32 v13, v2
	v_mov_b32_e32 v14, v2
	v_mov_b32_e32 v15, v2
	v_mov_b32_e32 v16, v2
	v_mov_b32_e32 v17, v2
	v_mov_b32_e32 v18, v2
	v_mov_b32_e32 v19, v2
	v_mov_b32_e32 v20, v2
	v_mov_b32_e32 v21, v2
	v_mov_b32_e32 v22, v2
	v_mov_b32_e32 v23, v2
	v_mov_b32_e32 v24, v2
	v_mov_b32_e32 v25, v2
	v_mov_b32_e32 v26, v2
	v_mov_b32_e32 v27, v2
	v_mov_b32_e32 v28, v2
	v_mov_b32_e32 v29, v2
	v_mov_b32_e32 v30, v2
	v_mov_b32_e32 v31, v2
	v_mov_b32_e32 v32, v2
	v_mov_b32_e32 v33, v2
	v_mov_b32_e32 v34, v2
	v_mov_b32_e32 v35, v2
	v_mov_b32_e32 v36, v2
	v_mov_b32_e32 v37, v2
	v_mov_b32_e32 v38, v2
	v_mov_b32_e32 v39, v2
	v_mov_b32_e32 v40, v2
	v_mov_b32_e32 v41, v2
	v_mov_b32_e32 v42, v2
	v_mov_b32_e32 v43, v2
	v_mov_b32_e32 v44, v2
	v_mov_b32_e32 v45, v2
	v_mov_b32_e32 v46, v2
	v_mov_b32_e32 v47, v2
	v_mov_b32_e32 v48, v2
	v_mov_b32_e32 v49, v2
	v_mov_b32_e32 v50, v2
	v_mov_b32_e32 v51, v2
	v_mov_b32_e32 v52, v2
	v_mov_b32_e32 v53, v2
	v_mov_b32_e32 v54, v2
	v_mov_b32_e32 v55, v2
	v_mov_b32_e32 v56, v2
	v_mov_b32_e32 v57, v2
	v_mov_b32_e32 v58, v2
	v_mov_b32_e32 v59, v2
	v_mov_b32_e32 v60, v2
	v_mov_b32_e32 v61, v2
	v_mov_b32_e32 v62, v2
	v_mov_b32_e32 v63, v2
	v_mov_b32_e32 v64, v2
	v_mov_b32_e32 v65, v2
	v_mov_b32_e32 v66, v2
	v_mov_b32_e32 v67, v2
	v_mov_b32_e32 v68, v2
	v_mov_b32_e32 v69, v2
	v_mov_b32_e32 v70, v2
	v_mov_b32_e32 v71, v2
	v_mov_b32_e32 v72, v2
	v_mov_b32_e32 v73, v2
	v_mov_b32_e32 v74, v2
	v_mov_b32_e32 v75, v2
	v_mov_b32_e32 v76, v2
	v_mov_b32_e32 v77, v2
	v_mov_b32_e32 v78, v2
	v_mov_b32_e32 v79, v2
	v_mov_b32_e32 v80, v2
	v_mov_b32_e32 v81, v2
	v_mov_b32_e32 v82, v2
	v_mov_b32_e32 v83, v2
	v_mov_b32_e32 v84, v2
	v_mov_b32_e32 v85, v2
	v_mov_b32_e32 v86, v2
	v_mov_b32_e32 v87, v2
	v_mov_b32_e32 v88, v2
	v_mov_b32_e32 v89, v2
	v_mov_b32_e32 v90, v2
	v_mov_b32_e32 v91, v2
	v_mov_b32_e32 v92, v2
	v_mov_b32_e32 v93, v2
	v_mov_b32_e32 v94, v2
	v_mov_b32_e32 v95, v2
	v_mov_b32_e32 v96, v2
	v_mov_b32_e32 v97, v2
	v_mov_b32_e32 v98, v2
	v_mov_b32_e32 v99, v2
	v_mov_b32_e32 v100, v2
	v_mov_b32_e32 v101, v2
	v_mov_b32_e32 v102, v2
	v_mov_b32_e32 v103, v2
	v_mov_b32_e32 v104, v2
	v_mov_b32_e32 v105, v2
	v_mov_b32_e32 v106, v2
	v_mov_b32_e32 v107, v2
	v_mov_b32_e32 v108, v2
	v_mov_b32_e32 v109, v2
	v_mov_b32_e32 v110, v2
	v_mov_b32_e32 v111, v2
	v_mov_b32_e32 v112, v2
	v_mov_b32_e32 v113, v2
	v_mov_b32_e32 v114, v2
	v_mov_b32_e32 v115, v2
	v_mov_b32_e32 v116, v2
	v_mov_b32_e32 v117, v2
	v_mov_b32_e32 v118, v2
	v_mov_b32_e32 v119, v2
	v_mov_b32_e32 v120, v2
	v_mov_b32_e32 v121, v2
	v_mov_b32_e32 v122, v2
	v_mov_b32_e32 v123, v2
	v_mov_b32_e32 v124, v2
	v_mov_b32_e32 v125, v2
	v_mov_b32_e32 v126, v2
	v_mov_b32_e32 v127, v2
	v_mov_b32_e32 v128, v2
	v_mov_b32_e32 v129, v2
	s_waitcnt vmcnt(0)
	s_barrier
	s_branch .LBB0_225

.LBB0_305:
	s_lshl_b32 s18, s15, 6
	s_and_b32 s18, s18, 0x1c0
	s_ashr_i32 s19, s15, 3
	s_add_i32 s18, s18, s19
	s_ashr_i32 s20, s18, 31
	s_lshr_b32 s20, s20, 27
	s_add_i32 s20, s18, s20
	s_ashr_i32 s20, s20, 5
	s_lshl_b32 s19, s19, 8
	s_lshl_b32 s21, s20, 11
	s_and_b32 s19, s19, 0x700
	s_or_b32 s22, s21, s19
	s_lshl_b32 s19, s20, 10
	s_lshl_b32 s18, s18, 5
	v_mov_b32_e32 v2, v176
	s_sub_i32 s18, s18, s19
	s_and_b32 s18, s18, 0xffffff00
	v_readfirstlane_b32 s19, v2
	v_lshlrev_b32_e32 v3, 4, v2
	v_and_b32_e32 v4, 32, v2
	v_bfe_i32 v5, v2, 3, 25
	v_lshrrev_b32_e32 v6, 2, v2
	s_lshl_b32 s19, s19, 4
	v_bfi_b32 v5, -16, v5, v6
	v_bitop3_b32 v3, v3, v4, 48 bitop3:0x6c
	s_and_b32 s23, s19, 0xfffffc00
	v_and_or_b32 v3, v2, 64, v3
	v_add_u32_e32 v4, s18, v5
	s_cmp_lg_u32 0, -1
	v_lshl_or_b32 v130, v4, 11, v3
	v_add_u32_e32 v4, s22, v5
	s_cselect_b32 s20, 0, 0
	s_add_i32 s23, s23, s20
	s_barrier
	v_lshl_or_b32 v131, v4, 11, v3
	s_mov_b32 m0, s23
	global_load_lds_dwordx4 v131, s[2:3]
	s_add_i32 s24, s23, 0x8000
	s_mov_b32 m0, s24
	global_load_lds_dwordx4 v130, s[8:9]
	s_add_i32 s20, s23, 0x2000
	s_add_i32 s25, s23, 0xa000
	v_add_u32_e32 v132, 0x20000, v131
	s_mov_b32 m0, s20
	global_load_lds_dwordx4 v132, s[2:3]
	s_add_u32 s20, s8, 0x20000
	s_addc_u32 s21, s9, 0
	s_mov_b32 m0, s25
	global_load_lds_dwordx4 v130, s[20:21]
	s_add_i32 s20, s23, 0x4000
	s_add_i32 s25, s23, 0xc000
	v_add_u32_e32 v133, 0x40000, v131
	s_mov_b32 m0, s20
	global_load_lds_dwordx4 v133, s[2:3]
	s_add_u32 s20, s8, 0x40000
	s_addc_u32 s21, s9, 0
	s_mov_b32 m0, s25
	global_load_lds_dwordx4 v130, s[20:21]
	s_add_i32 s20, s23, 0x6000
	s_add_i32 s25, s23, 0xe000
	v_and_b32_e32 v3, 15, v2
	v_lshlrev_b32_e32 v5, 2, v2
	v_add_u32_e32 v134, 0x60000, v131
	s_mov_b32 m0, s20
	global_load_lds_dwordx4 v134, s[2:3]
	s_add_u32 s20, s8, 0x60000
	v_and_b32_e32 v4, 48, v2
	v_lshlrev_b32_e32 v3, 6, v3
	v_and_b32_e32 v5, 32, v5
	s_addc_u32 s21, s9, 0
	s_mov_b32 m0, s25
	global_load_lds_dwordx4 v130, s[20:21]
	v_bitop3_b32 v135, v3, v5, v4 bitop3:0x36
	v_lshlrev_b32_e32 v3, 7, v2
	v_lshlrev_b32_e32 v2, 6, v2
	v_and_b32_e32 v137, 0xffffc000, v2
	v_and_b32_e32 v2, 0x3c0, v2
	v_bitop3_b32 v138, v2, v5, v4 bitop3:0x36
	v_mov_b32_e32 v2, 0
	s_mov_b32 s19, 0
	v_and_b32_e32 v136, 0x6000, v3
	s_mov_b64 s[42:43], s[40:41]
	s_waitcnt lgkmcnt(0)
	s_mov_b64 s[44:45], s[16:17]
	v_mov_b32_e32 v3, v2
	v_mov_b32_e32 v4, v2
	v_mov_b32_e32 v5, v2
	v_mov_b32_e32 v6, v2
	v_mov_b32_e32 v7, v2
	v_mov_b32_e32 v8, v2
	v_mov_b32_e32 v9, v2
	v_mov_b32_e32 v10, v2
	v_mov_b32_e32 v11, v2
	v_mov_b32_e32 v12, v2
	v_mov_b32_e32 v13, v2
	v_mov_b32_e32 v14, v2
	v_mov_b32_e32 v15, v2
	v_mov_b32_e32 v16, v2
	v_mov_b32_e32 v17, v2
	v_mov_b32_e32 v18, v2
	v_mov_b32_e32 v19, v2
	v_mov_b32_e32 v20, v2
	v_mov_b32_e32 v21, v2
	v_mov_b32_e32 v22, v2
	v_mov_b32_e32 v23, v2
	v_mov_b32_e32 v24, v2
	v_mov_b32_e32 v25, v2
	v_mov_b32_e32 v26, v2
	v_mov_b32_e32 v27, v2
	v_mov_b32_e32 v28, v2
	v_mov_b32_e32 v29, v2
	v_mov_b32_e32 v30, v2
	v_mov_b32_e32 v31, v2
	v_mov_b32_e32 v32, v2
	v_mov_b32_e32 v33, v2
	v_mov_b32_e32 v34, v2
	v_mov_b32_e32 v35, v2
	v_mov_b32_e32 v36, v2
	v_mov_b32_e32 v37, v2
	v_mov_b32_e32 v38, v2
	v_mov_b32_e32 v39, v2
	v_mov_b32_e32 v40, v2
	v_mov_b32_e32 v41, v2
	v_mov_b32_e32 v42, v2
	v_mov_b32_e32 v43, v2
	v_mov_b32_e32 v44, v2
	v_mov_b32_e32 v45, v2
	v_mov_b32_e32 v46, v2
	v_mov_b32_e32 v47, v2
	v_mov_b32_e32 v48, v2
	v_mov_b32_e32 v49, v2
	v_mov_b32_e32 v50, v2
	v_mov_b32_e32 v51, v2
	v_mov_b32_e32 v52, v2
	v_mov_b32_e32 v53, v2
	v_mov_b32_e32 v54, v2
	v_mov_b32_e32 v55, v2
	v_mov_b32_e32 v56, v2
	v_mov_b32_e32 v57, v2
	v_mov_b32_e32 v58, v2
	v_mov_b32_e32 v59, v2
	v_mov_b32_e32 v60, v2
	v_mov_b32_e32 v61, v2
	v_mov_b32_e32 v62, v2
	v_mov_b32_e32 v63, v2
	v_mov_b32_e32 v64, v2
	v_mov_b32_e32 v65, v2
	v_mov_b32_e32 v66, v2
	v_mov_b32_e32 v67, v2
	v_mov_b32_e32 v68, v2
	v_mov_b32_e32 v69, v2
	v_mov_b32_e32 v70, v2
	v_mov_b32_e32 v71, v2
	v_mov_b32_e32 v72, v2
	v_mov_b32_e32 v73, v2
	v_mov_b32_e32 v74, v2
	v_mov_b32_e32 v75, v2
	v_mov_b32_e32 v76, v2
	v_mov_b32_e32 v77, v2
	v_mov_b32_e32 v78, v2
	v_mov_b32_e32 v79, v2
	v_mov_b32_e32 v80, v2
	v_mov_b32_e32 v81, v2
	v_mov_b32_e32 v82, v2
	v_mov_b32_e32 v83, v2
	v_mov_b32_e32 v84, v2
	v_mov_b32_e32 v85, v2
	v_mov_b32_e32 v86, v2
	v_mov_b32_e32 v87, v2
	v_mov_b32_e32 v88, v2
	v_mov_b32_e32 v89, v2
	v_mov_b32_e32 v90, v2
	v_mov_b32_e32 v91, v2
	v_mov_b32_e32 v92, v2
	v_mov_b32_e32 v93, v2
	v_mov_b32_e32 v94, v2
	v_mov_b32_e32 v95, v2
	v_mov_b32_e32 v96, v2
	v_mov_b32_e32 v97, v2
	v_mov_b32_e32 v98, v2
	v_mov_b32_e32 v99, v2
	v_mov_b32_e32 v100, v2
	v_mov_b32_e32 v101, v2
	v_mov_b32_e32 v102, v2
	v_mov_b32_e32 v103, v2
	v_mov_b32_e32 v104, v2
	v_mov_b32_e32 v105, v2
	v_mov_b32_e32 v106, v2
	v_mov_b32_e32 v107, v2
	v_mov_b32_e32 v108, v2
	v_mov_b32_e32 v109, v2
	v_mov_b32_e32 v110, v2
	v_mov_b32_e32 v111, v2
	v_mov_b32_e32 v112, v2
	v_mov_b32_e32 v113, v2
	v_mov_b32_e32 v114, v2
	v_mov_b32_e32 v115, v2
	v_mov_b32_e32 v116, v2
	v_mov_b32_e32 v117, v2
	v_mov_b32_e32 v118, v2
	v_mov_b32_e32 v119, v2
	v_mov_b32_e32 v120, v2
	v_mov_b32_e32 v121, v2
	v_mov_b32_e32 v122, v2
	v_mov_b32_e32 v123, v2
	v_mov_b32_e32 v124, v2
	v_mov_b32_e32 v125, v2
	v_mov_b32_e32 v126, v2
	v_mov_b32_e32 v127, v2
	v_mov_b32_e32 v128, v2
	v_mov_b32_e32 v129, v2
	v_or_b32_e32 v139, 0x800, v137
	v_or_b32_e32 v140, 0x1000, v137
	v_or_b32_e32 v141, 0x1800, v137
	v_or_b32_e32 v142, 0x2000, v137
	v_or_b32_e32 v143, 0x2800, v137
	v_or_b32_e32 v144, 0x3000, v137
	v_or_b32_e32 v145, 0x3800, v137
	s_waitcnt vmcnt(0)
	s_barrier
	s_branch .LBB0_307

.LBB0_630:
	s_lshl_b32 s10, s21, 6
	s_and_b32 s10, s10, 0x1c0
	s_ashr_i32 s11, s21, 3
	s_add_i32 s10, s10, s11
	s_ashr_i32 s12, s10, 31
	s_lshr_b32 s12, s12, 27
	s_add_i32 s12, s10, s12
	s_ashr_i32 s12, s12, 5
	s_lshl_b32 s11, s11, 8
	s_lshl_b32 s13, s12, 11
	s_and_b32 s11, s11, 0x700
	v_mov_b32_e32 v2, v176
	s_or_b32 s22, s13, s11
	s_lshl_b32 s11, s12, 10
	s_lshl_b32 s10, s10, 5
	s_sub_i32 s10, s10, s11
	v_lshlrev_b32_e32 v3, 4, v2
	v_and_b32_e32 v4, 32, v2
	v_bfe_i32 v5, v2, 3, 25
	v_lshrrev_b32_e32 v6, 2, v2
	v_bitop3_b32 v3, v3, v4, 48 bitop3:0x6c
	s_and_b32 s10, s10, 0xffffff00
	v_bfi_b32 v5, -16, v5, v6
	v_lshrrev_b32_e32 v6, 1, v2
	v_lshrrev_b32_e32 v3, 1, v3
	v_and_or_b32 v3, v6, 32, v3
	v_add_u32_e32 v6, s10, v5
	v_readfirstlane_b32 s11, v2
	v_mul_lo_u32 v6, v6, s15
	s_lshl_b32 s11, s11, 4
	v_lshlrev_b32_e32 v4, 1, v3
	v_or_b32_e32 v3, v6, v3
	s_and_b32 s23, s11, 0xfffffc00
	v_lshlrev_b32_e32 v130, 1, v3
	v_add_u32_e32 v3, s22, v5
	s_cmp_lg_u32 0, -1
	s_cselect_b32 s12, 0, 0
	v_mul_lo_u32 v3, v3, s18
	s_add_i32 s23, s23, s12
	s_waitcnt lgkmcnt(0)
	s_barrier
	v_or_b32_e32 v131, v3, v4
	s_mov_b32 m0, s23
	global_load_lds_dwordx4 v131, s[2:3]
	s_add_i32 s24, s23, 0x8000
	s_mov_b32 m0, s24
	global_load_lds_dwordx4 v130, s[4:5]
	s_add_i32 s12, s23, 0x2000
	v_add_u32_e32 v3, s17, v3
	s_add_i32 s25, s23, 0xa000
	v_or_b32_e32 v132, v3, v4
	s_mov_b32 m0, s12
	global_load_lds_dwordx4 v132, s[2:3]
	s_add_u32 s12, s4, s17
	s_addc_u32 s13, s5, 0
	s_mov_b32 m0, s25
	global_load_lds_dwordx4 v130, s[12:13]
	s_add_i32 s12, s23, 0x4000
	v_add_u32_e32 v3, s17, v3
	s_add_i32 s25, s23, 0xc000
	v_or_b32_e32 v133, v3, v4
	s_mov_b32 m0, s12
	global_load_lds_dwordx4 v133, s[2:3]
	s_add_u32 s12, s4, s19
	v_add_u32_e32 v3, s17, v3
	s_addc_u32 s13, s5, 0
	s_mov_b32 m0, s25
	global_load_lds_dwordx4 v130, s[12:13]
	s_add_i32 s12, s23, 0x6000
	v_or_b32_e32 v134, v3, v4
	s_add_i32 s25, s23, 0xe000
	v_and_b32_e32 v3, 15, v2
	v_lshlrev_b32_e32 v5, 2, v2
	s_mov_b32 m0, s12
	global_load_lds_dwordx4 v134, s[2:3]
	s_add_u32 s12, s4, s20
	v_and_b32_e32 v4, 48, v2
	v_lshlrev_b32_e32 v3, 6, v3
	v_and_b32_e32 v5, 32, v5
	s_addc_u32 s13, s5, 0
	s_mov_b32 m0, s25
	global_load_lds_dwordx4 v130, s[12:13]
	v_bitop3_b32 v135, v3, v5, v4 bitop3:0x36
	v_lshlrev_b32_e32 v3, 7, v2
	v_lshlrev_b32_e32 v2, 6, v2
	v_and_b32_e32 v137, 0xffffc000, v2
	v_and_b32_e32 v2, 0x3c0, v2
	v_bitop3_b32 v139, v2, v5, v4 bitop3:0x36
	v_mov_b32_e32 v2, 0
	s_mov_b32 s11, 0
	v_and_b32_e32 v136, 0x6000, v3
	v_or_b32_e32 v138, 0x800, v137
	v_or_b32_e32 v140, 0x1000, v137
	v_or_b32_e32 v141, 0x1800, v137
	v_or_b32_e32 v142, 0x2000, v137
	v_or_b32_e32 v143, 0x2800, v137
	v_or_b32_e32 v144, 0x3000, v137
	v_or_b32_e32 v145, 0x3800, v137
	s_mov_b32 s86, 64
	v_mov_b32_e32 v3, v2
	v_mov_b32_e32 v4, v2
	v_mov_b32_e32 v5, v2
	v_mov_b32_e32 v6, v2
	v_mov_b32_e32 v7, v2
	v_mov_b32_e32 v8, v2
	v_mov_b32_e32 v9, v2
	v_mov_b32_e32 v10, v2
	v_mov_b32_e32 v11, v2
	v_mov_b32_e32 v12, v2
	v_mov_b32_e32 v13, v2
	v_mov_b32_e32 v14, v2
	v_mov_b32_e32 v15, v2
	v_mov_b32_e32 v16, v2
	v_mov_b32_e32 v17, v2
	v_mov_b32_e32 v18, v2
	v_mov_b32_e32 v19, v2
	v_mov_b32_e32 v20, v2
	v_mov_b32_e32 v21, v2
	v_mov_b32_e32 v22, v2
	v_mov_b32_e32 v23, v2
	v_mov_b32_e32 v24, v2
	v_mov_b32_e32 v25, v2
	v_mov_b32_e32 v26, v2
	v_mov_b32_e32 v27, v2
	v_mov_b32_e32 v28, v2
	v_mov_b32_e32 v29, v2
	v_mov_b32_e32 v30, v2
	v_mov_b32_e32 v31, v2
	v_mov_b32_e32 v32, v2
	v_mov_b32_e32 v33, v2
	v_mov_b32_e32 v34, v2
	v_mov_b32_e32 v35, v2
	v_mov_b32_e32 v36, v2
	v_mov_b32_e32 v37, v2
	v_mov_b32_e32 v38, v2
	v_mov_b32_e32 v39, v2
	v_mov_b32_e32 v40, v2
	v_mov_b32_e32 v41, v2
	v_mov_b32_e32 v42, v2
	v_mov_b32_e32 v43, v2
	v_mov_b32_e32 v44, v2
	v_mov_b32_e32 v45, v2
	v_mov_b32_e32 v46, v2
	v_mov_b32_e32 v47, v2
	v_mov_b32_e32 v48, v2
	v_mov_b32_e32 v49, v2
	v_mov_b32_e32 v50, v2
	v_mov_b32_e32 v51, v2
	v_mov_b32_e32 v52, v2
	v_mov_b32_e32 v53, v2
	v_mov_b32_e32 v54, v2
	v_mov_b32_e32 v55, v2
	v_mov_b32_e32 v56, v2
	v_mov_b32_e32 v57, v2
	v_mov_b32_e32 v58, v2
	v_mov_b32_e32 v59, v2
	v_mov_b32_e32 v60, v2
	v_mov_b32_e32 v61, v2
	v_mov_b32_e32 v62, v2
	v_mov_b32_e32 v63, v2
	v_mov_b32_e32 v64, v2
	v_mov_b32_e32 v65, v2
	v_mov_b32_e32 v66, v2
	v_mov_b32_e32 v67, v2
	v_mov_b32_e32 v68, v2
	v_mov_b32_e32 v69, v2
	v_mov_b32_e32 v70, v2
	v_mov_b32_e32 v71, v2
	v_mov_b32_e32 v72, v2
	v_mov_b32_e32 v73, v2
	v_mov_b32_e32 v74, v2
	v_mov_b32_e32 v75, v2
	v_mov_b32_e32 v76, v2
	v_mov_b32_e32 v77, v2
	v_mov_b32_e32 v78, v2
	v_mov_b32_e32 v79, v2
	v_mov_b32_e32 v80, v2
	v_mov_b32_e32 v81, v2
	v_mov_b32_e32 v82, v2
	v_mov_b32_e32 v83, v2
	v_mov_b32_e32 v84, v2
	v_mov_b32_e32 v85, v2
	v_mov_b32_e32 v86, v2
	v_mov_b32_e32 v87, v2
	v_mov_b32_e32 v88, v2
	v_mov_b32_e32 v89, v2
	v_mov_b32_e32 v90, v2
	v_mov_b32_e32 v91, v2
	v_mov_b32_e32 v92, v2
	v_mov_b32_e32 v93, v2
	v_mov_b32_e32 v94, v2
	v_mov_b32_e32 v95, v2
	v_mov_b32_e32 v96, v2
	v_mov_b32_e32 v97, v2
	v_mov_b32_e32 v98, v2
	v_mov_b32_e32 v99, v2
	v_mov_b32_e32 v100, v2
	v_mov_b32_e32 v101, v2
	v_mov_b32_e32 v102, v2
	v_mov_b32_e32 v103, v2
	v_mov_b32_e32 v104, v2
	v_mov_b32_e32 v105, v2
	v_mov_b32_e32 v106, v2
	v_mov_b32_e32 v107, v2
	v_mov_b32_e32 v108, v2
	v_mov_b32_e32 v109, v2
	v_mov_b32_e32 v110, v2
	v_mov_b32_e32 v111, v2
	v_mov_b32_e32 v112, v2
	v_mov_b32_e32 v113, v2
	v_mov_b32_e32 v114, v2
	v_mov_b32_e32 v115, v2
	v_mov_b32_e32 v116, v2
	v_mov_b32_e32 v117, v2
	v_mov_b32_e32 v118, v2
	v_mov_b32_e32 v119, v2
	v_mov_b32_e32 v120, v2
	v_mov_b32_e32 v121, v2
	v_mov_b32_e32 v122, v2
	v_mov_b32_e32 v123, v2
	v_mov_b32_e32 v124, v2
	v_mov_b32_e32 v125, v2
	v_mov_b32_e32 v126, v2
	v_mov_b32_e32 v127, v2
	v_mov_b32_e32 v128, v2
	v_mov_b32_e32 v129, v2
	s_waitcnt vmcnt(0)
	s_barrier
	s_branch .LBB0_632

	.amdhsa_kernel _Z9yoco_mega6Params
		.amdhsa_group_segment_fixed_size 0
		.amdhsa_private_segment_fixed_size 0
		.amdhsa_kernarg_size 560
		.amdhsa_user_sgpr_count 2
		.amdhsa_user_sgpr_dispatch_ptr 0
		.amdhsa_user_sgpr_queue_ptr 0
		.amdhsa_user_sgpr_kernarg_segment_ptr 1
		.amdhsa_user_sgpr_dispatch_id 0
		.amdhsa_user_sgpr_kernarg_preload_length 0
		.amdhsa_user_sgpr_kernarg_preload_offset 0
		.amdhsa_user_sgpr_private_segment_size 0
		.amdhsa_uses_dynamic_stack 0
		.amdhsa_enable_private_segment 0
		.amdhsa_system_sgpr_workgroup_id_x 1
		.amdhsa_system_sgpr_workgroup_id_y 0
		.amdhsa_system_sgpr_workgroup_id_z 0
		.amdhsa_system_sgpr_workgroup_info 0
		.amdhsa_system_vgpr_workitem_id 2
		.amdhsa_next_free_vgpr 252
		.amdhsa_next_free_sgpr 100
		.amdhsa_accum_offset 252
		.amdhsa_reserve_vcc 1
		.amdhsa_float_round_mode_32 0
		.amdhsa_float_round_mode_16_64 0
		.amdhsa_float_denorm_mode_32 3
		.amdhsa_float_denorm_mode_16_64 3
		.amdhsa_dx10_clamp 1
		.amdhsa_ieee_mode 1
		.amdhsa_fp16_overflow 0
		.amdhsa_tg_split 0
		.amdhsa_exception_fp_ieee_invalid_op 0
		.amdhsa_exception_fp_denorm_src 0
		.amdhsa_exception_fp_ieee_div_zero 0
		.amdhsa_exception_fp_ieee_overflow 0
		.amdhsa_exception_fp_ieee_underflow 0
		.amdhsa_exception_fp_ieee_inexact 0
		.amdhsa_exception_int_div_zero 0
	.end_amdhsa_kernel

amdhsa.kernels:
  - .agpr_count:     0
    .args:
      - .offset:         0
        .size:           304
        .value_kind:     by_value
      - .offset:         304
        .size:           4
        .value_kind:     hidden_block_count_x
      - .offset:         308
        .size:           4
        .value_kind:     hidden_block_count_y
      - .offset:         312
        .size:           4
        .value_kind:     hidden_block_count_z
      - .offset:         316
        .size:           2
        .value_kind:     hidden_group_size_x
      - .offset:         318
        .size:           2
        .value_kind:     hidden_group_size_y
      - .offset:         320
        .size:           2
        .value_kind:     hidden_group_size_z
      - .offset:         322
        .size:           2
        .value_kind:     hidden_remainder_x
      - .offset:         324
        .size:           2
        .value_kind:     hidden_remainder_y
      - .offset:         326
        .size:           2
        .value_kind:     hidden_remainder_z
      - .offset:         344
        .size:           8
        .value_kind:     hidden_global_offset_x
      - .offset:         352
        .size:           8
        .value_kind:     hidden_global_offset_y
      - .offset:         360
        .size:           8
        .value_kind:     hidden_global_offset_z
      - .offset:         368
        .size:           2
        .value_kind:     hidden_grid_dims
      - .offset:         392
        .size:           8
        .value_kind:     hidden_multigrid_sync_arg
      - .offset:         424
        .size:           4
        .value_kind:     hidden_dynamic_lds_size
    .group_segment_fixed_size: 0
    .kernarg_segment_align: 8
    .kernarg_segment_size: 560
    .language:       OpenCL C
    .language_version:
      - 2
      - 0
    .max_flat_workgroup_size: 512
    .name:           _Z9yoco_mega6Params
    .private_segment_fixed_size: 0
    .sgpr_count:     106
    .sgpr_spill_count: 127
    .symbol:         _Z9yoco_mega6Params.kd
    .uniform_work_group_size: 1
    .uses_dynamic_stack: false
    .vgpr_count:     252
    .vgpr_spill_count: 0
    .wavefront_size: 64
